# in-projection sk/sv (f32) epilogue stores: chunk pairs parked and exchanged between rows r / r+8 (DPP row_ror) so each store writes whole 128 B lines; counted waits tightened by one
# baseline (speedup 1.0000x reference)
; DI float sum16(const float* p) { const f32x4* q = (const f32x4*)p; f32x4 a = q[0], b = q[1], c = q[2], d = q[3]; f32x4 s = (a + b) + (c + d); return (s[0] + s[1]) + (s[2] + s[3]); }
;     template <int PN> DI void body(AccRef acc, const Unit& u, int wr, int wc, int fr, int fq) const {
;     ...
;         for (int ai = 0; ai < 2; ++ai) {
;             const int rb_ = u.pm * 256 + ai * 128 + wr * 64 + fr;
; #pragma unroll
;             for (int m = 0; m < 4; ++m) rinvh[ai][m] = rsqrtf(sum16(ssq + (size_t)(rb_ + 16 * m + zdep) * 16) * (1.f / 1024.f) + EPS);
;             asm volatile("v_mov_b32 %0, 0" : "=v"(zdep) : "v"(rinvh[ai][0]), "v"(rinvh[ai][1]), "v"(rinvh[ai][2]), "v"(rinvh[ai][3]));
;         }
; #pragma unroll
;         for (int ai = 0; ai < 2; ++ai) {
;             const int rb_ = u.pm * 256 + ai * 128 + wr * 64 + fr;
;             int mb_, p_, k_; row_info(rb_, mb_, p_, k_);
; #pragma unroll
;             for (int bj = 0; bj < 2; ++bj)
; #pragma unroll
;                 for (int n = 0; n < 2; ++n) cvh[ai][bj][n] = *(const f32x4*)(cv + (size_t)(mb_ + zdep) * NIN + PN * 256 + bj * 128 + cl + 4 * n);
;         }
;     DI void operator()(AccRef acc, const Unit& u, int wr, int wc, int fr, int fq) const {
;         switch (u.pn) {
;             case 0: body<0>(acc, u, wr, wc, fr, fq); break;
;             case 1: body<1>(acc, u, wr, wc, fr, fq); break;
;             case 2: body<2>(acc, u, wr, wc, fr, fq); break;
;             case 3: body<3>(acc, u, wr, wc, fr, fq); break;
;             case 4: body<4>(acc, u, wr, wc, fr, fq); break;
;             case 5: body<5>(acc, u, wr, wc, fr, fq); break;
;             case 6: body<6>(acc, u, wr, wc, fr, fq); break;
;             case 7: body<7>(acc, u, wr, wc, fr, fq); break;
;             case 8: body<8>(acc, u, wr, wc, fr, fq); break;
;             default: body<9>(acc, u, wr, wc, fr, fq); break;
;         }
.LBB0_353:
	s_mov_b32 s2, s21
	v_mbcnt_lo_u32_b32 v128, -1, 0
	v_mbcnt_hi_u32_b32 v128, -1, v128
	s_mov_b32 s66, s36
	v_and_b32_e32 v214, 15, v128
	v_bfe_u32 v213, v128, 4, 2
	s_mov_b32 s53, s27
	s_lshl_b32 s22, s53, 6
	s_lshl_b32 s23, s34, 8
	s_add_i32 s22, s22, s23
	v_add_u32_e32 v244, s22, v214
	v_lshlrev_b32_e32 v244, 6, v244
	v_lshl_add_u32 v244, v213, 4, v244
	global_load_dwordx4 v[228:231], v244, s[56:57]
	global_load_dwordx4 v[232:235], v244, s[56:57] offset:1024
	global_load_dwordx4 v[236:239], v244, s[56:57] offset:2048
	global_load_dwordx4 v[240:243], v244, s[56:57] offset:3072
	v_add_u32_e32 v244, 0x2000, v244
	global_load_dwordx4 v[216:219], v244, s[56:57]
	global_load_dwordx4 v[220:223], v244, s[56:57] offset:1024
	global_load_dwordx4 v[142:145], v244, s[56:57] offset:2048
	global_load_dwordx4 v[146:149], v244, s[56:57] offset:3072
	v_mov_b32_e32 v245, 0x3a800000
	s_waitcnt vmcnt(4)
	v_pk_add_f32 v[228:229], v[228:229], v[230:231]
	v_pk_add_f32 v[232:233], v[232:233], v[234:235]
	v_pk_add_f32 v[236:237], v[236:237], v[238:239]
	v_pk_add_f32 v[240:241], v[240:241], v[242:243]
	v_add_f32_e32 v228, v228, v229
	v_add_f32_e32 v232, v232, v233
	v_add_f32_e32 v236, v236, v237
	v_add_f32_e32 v240, v240, v241
	v_mov_b32_e32 v229, v228
	v_mov_b32_e32 v233, v232
	v_mov_b32_e32 v237, v236
	v_mov_b32_e32 v241, v240
	s_waitcnt vmcnt(0)
	v_pk_add_f32 v[216:217], v[216:217], v[218:219]
	v_pk_add_f32 v[220:221], v[220:221], v[222:223]
	v_pk_add_f32 v[142:143], v[142:143], v[144:145]
	v_pk_add_f32 v[146:147], v[146:147], v[148:149]
	v_add_f32_e32 v216, v216, v217
	v_add_f32_e32 v220, v220, v221
	v_add_f32_e32 v142, v142, v143
	v_add_f32_e32 v146, v146, v147
	v_mov_b32_e32 v217, v216
	v_mov_b32_e32 v221, v220
	v_mov_b32_e32 v143, v142
	v_mov_b32_e32 v147, v146
	s_nop 1
	v_permlane32_swap_b32_e32 v228, v229
	v_permlane32_swap_b32_e32 v232, v233
	v_permlane32_swap_b32_e32 v236, v237
	v_permlane32_swap_b32_e32 v240, v241
	v_permlane32_swap_b32_e32 v216, v217
	v_permlane32_swap_b32_e32 v220, v221
	v_permlane32_swap_b32_e32 v142, v143
	v_permlane32_swap_b32_e32 v146, v147
	v_add_f32_e32 v228, v228, v229
	v_add_f32_e32 v232, v232, v233
	v_add_f32_e32 v236, v236, v237
	v_add_f32_e32 v240, v240, v241
	v_add_f32_e32 v216, v216, v217
	v_add_f32_e32 v220, v220, v221
	v_add_f32_e32 v142, v142, v143
	v_add_f32_e32 v146, v146, v147
	v_mov_b32_e32 v229, v228
	v_mov_b32_e32 v233, v232
	v_mov_b32_e32 v237, v236
	v_mov_b32_e32 v241, v240
	v_mov_b32_e32 v217, v216
	v_mov_b32_e32 v221, v220
	v_mov_b32_e32 v143, v142
	v_mov_b32_e32 v147, v146
	s_nop 1
	v_permlane16_swap_b32_e32 v228, v229
	v_permlane16_swap_b32_e32 v232, v233
	v_permlane16_swap_b32_e32 v236, v237
	v_permlane16_swap_b32_e32 v240, v241
	v_permlane16_swap_b32_e32 v216, v217
	v_permlane16_swap_b32_e32 v220, v221
	v_permlane16_swap_b32_e32 v142, v143
	v_permlane16_swap_b32_e32 v146, v147
	v_add_f32_e32 v228, v228, v229
	v_add_f32_e32 v232, v232, v233
	v_add_f32_e32 v236, v236, v237
	v_add_f32_e32 v240, v240, v241
	v_add_f32_e32 v216, v216, v217
	v_add_f32_e32 v220, v220, v221
	v_add_f32_e32 v142, v142, v143
	v_add_f32_e32 v146, v146, v147
	v_fmaak_f32 v228, v245, v228, 0x358637bd
	v_fmaak_f32 v232, v245, v232, 0x358637bd
	v_fmaak_f32 v236, v245, v236, 0x358637bd
	v_fmaak_f32 v240, v245, v240, 0x358637bd
	v_fmaak_f32 v216, v245, v216, 0x358637bd
	v_fmaak_f32 v220, v245, v220, 0x358637bd
	v_fmaak_f32 v142, v245, v142, 0x358637bd
	v_fmaak_f32 v146, v245, v146, 0x358637bd
	v_rsq_f32_e32 v244, v228
	v_rsq_f32_e32 v245, v232
	v_rsq_f32_e32 v246, v236
	v_rsq_f32_e32 v247, v240
	v_rsq_f32_e32 v248, v216
	v_rsq_f32_e32 v249, v220
	v_rsq_f32_e32 v250, v142
	v_rsq_f32_e32 v251, v146
	s_mov_b64 s[2:3], -1
	s_mov_b64 s[8:9], 0
	s_cmp_lt_i32 s52, 4
	s_mov_b64 s[94:95], 0
	s_cbranch_scc1 .LBB0_372
	s_cmp_gt_i32 s52, 5
	s_cbranch_scc0 .LBB0_366
	s_cmp_gt_i32 s52, 6
	s_cbranch_scc0 .LBB0_363
	s_cmp_gt_i32 s52, 7
	s_cbranch_scc0 .LBB0_360
	s_cmp_eq_u32 s52, 8
	s_mov_b64 s[94:95], -1
	s_cbranch_scc0 .LBB0_359
	s_lshl_b32 s2, s53, 6
	s_lshl_b32 s3, s34, 8
	s_add_i32 s2, s2, s3
	v_add_u32_e32 v160, s2, v214
	v_ashrrev_i32_e32 v161, 31, v160
	v_lshlrev_b64 v[128:129], 6, v[160:161]
	v_lshl_add_u64 v[140:141], s[56:57], 0, v[128:129]
	s_nop 0
	v_add_u32_e32 v168, 16, v160
	v_ashrrev_i32_e32 v169, 31, v168
	s_mov_b32 s2, 0x358637bd
	s_mov_b32 s4, 0x3a800000
	v_add_u32_e32 v164, 32, v160
	v_ashrrev_i32_e32 v165, 31, v164
	v_add_u32_e32 v166, 48, v160
	v_ashrrev_i32_e32 v167, 31, v166
	v_add_u32_e32 v163, 0x80, v160
	v_add_u32_e32 v173, 0xffffc000, v160
	s_movk_i32 s6, 0x4000
	s_mov_b64 s[12:13], 0x126000
	v_add_u32_e32 v171, 0xffffc080, v160
	v_mov_b32_e32 v175, 0x6800000
	s_mov_b64 s[94:95], 0
	s_nop 0
	v_lshlrev_b64 v[128:129], 6, v[168:169]
	v_lshl_add_u64 v[140:141], s[56:57], 0, v[128:129]
	s_nop 0
	s_nop 0
	v_mov_b64_e32 v[128:129], s[2:3]
	s_nop 0
	s_nop 0
	s_nop 0
	v_mov_b32_e32 v188, v244
	s_nop 0
	v_mov_b32_e32 v162, v245
	v_lshlrev_b64 v[130:131], 6, v[164:165]
	v_lshl_add_u64 v[142:143], s[56:57], 0, v[130:131]
	s_nop 0
	s_nop 0
	v_lshlrev_b64 v[130:131], 6, v[166:167]
	v_lshl_add_u64 v[142:143], s[56:57], 0, v[130:131]
	s_nop 0
	s_nop 0
	s_nop 0
	s_nop 0
	s_nop 0
	s_nop 0
	v_mov_b32_e32 v170, v246
	s_nop 0
	v_mov_b32_e32 v174, v247
	v_mov_b32 v130, 0
	s_nop 0
	v_add_u32_e32 v130, v130, v163
	v_ashrrev_i32_e32 v131, 31, v130
	v_lshlrev_b64 v[132:133], 6, v[130:131]
	v_lshl_add_u64 v[144:145], s[56:57], 0, v[132:133]
	s_nop 0
	s_nop 0
	v_add_u32_e32 v132, 16, v130
	v_ashrrev_i32_e32 v133, 31, v132
	v_lshlrev_b64 v[132:133], 6, v[132:133]
	v_lshl_add_u64 v[144:145], s[56:57], 0, v[132:133]
	s_nop 0
	s_nop 0
	s_nop 0
;     template <int PN> DI void body(AccRef acc, const Unit& u, int wr, int wc, int fr, int fq) const {
;     ...
;                     float* lo = orow(out, l, row, PN == 8 ? O_PSK : O_PSV, PN == 8 ? O_SSK : O_SSV, 256);
; #pragma unroll
;                     for (int bj = 0; bj < 2; ++bj) {
;                         *(f32x4*)(lo + bj * 128 + cl) = (f32x4){v[bj][0], v[bj][1], v[bj][2], v[bj][3]};
;                         *(f32x4*)(lo + bj * 128 + cl + 4) = (f32x4){v[bj][4], v[bj][5], v[bj][6], v[bj][7]};
;                     }
	s_nop 0
	s_nop 0
	s_nop 0
	v_mov_b32_e32 v190, v248
	s_nop 0
	v_mov_b32_e32 v172, v249
	v_add_u32_e32 v132, 32, v130
	v_ashrrev_i32_e32 v133, 31, v132
	v_lshlrev_b64 v[132:133], 6, v[132:133]
	v_lshl_add_u64 v[144:145], s[56:57], 0, v[132:133]
	s_nop 0
	v_add_u32_e32 v130, 48, v130
	v_ashrrev_i32_e32 v131, 31, v130
	v_lshlrev_b64 v[130:131], 6, v[130:131]
	v_lshl_add_u64 v[142:143], s[56:57], 0, v[130:131]
	s_nop 0
	s_nop 0
	s_nop 0
	v_lshrrev_b32_e32 v131, 6, v173
	v_add_u32_e32 v131, 8, v131
	s_nop 0
	v_mov_b32_e32 v192, v250
	s_lshl_b32 s2, s66, 5
	v_ashrrev_i32_e32 v130, 11, v160
	v_mov_b32_e32 v194, v251
	v_lshl_add_u32 v128, v213, 3, s2
	v_cmp_gt_i32_e64 s[2:3], s6, v160
	v_mov_b32 v134, 0
	v_ashrrev_i32_e32 v129, 31, v128
	v_lshlrev_b64 v[196:197], 2, v[128:129]
	v_cndmask_b32_e64 v130, v131, v130, s[2:3]
	v_add_u32_e32 v132, v134, v130
	v_mov_b64_e32 v[130:131], s[10:11]
	v_mad_i64_i32 v[132:133], s[4:5], v132, s51, v[130:131]
	v_lshl_add_u64 v[128:129], v[132:133], 0, v[196:197]
	v_lshl_add_u64 v[132:133], v[128:129], 0, s[12:13]
	v_add_co_u32_e32 v128, vcc, s62, v128
	v_cndmask_b32_e64 v198, v173, v160, s[2:3]
	s_nop 0
	v_addc_co_u32_e32 v129, vcc, 0, v129, vcc
	global_load_dwordx4 v[152:155], v[128:129], off
	global_load_dwordx4 v[156:159], v[132:133], off offset:16
	global_load_dwordx4 v[144:147], v[132:133], off offset:528
	global_load_dwordx4 v[148:151], v[132:133], off offset:512
	v_lshrrev_b32_e32 v129, 6, v171
	v_cmp_gt_i32_e32 vcc, s6, v163
	v_ashrrev_i32_e32 v128, 11, v163
	v_add_u32_e32 v129, 8, v129
	v_cndmask_b32_e32 v128, v129, v128, vcc
	v_add_u32_e32 v128, v134, v128
	v_mad_i64_i32 v[128:129], s[4:5], v128, s51, v[130:131]
	v_lshl_add_u64 v[128:129], v[128:129], 0, v[196:197]
	v_lshl_add_u64 v[132:133], v[128:129], 0, s[12:13]
	v_add_co_u32_e64 v128, s[4:5], s62, v128
	v_mov_b32_e32 v173, 0xab98000
	s_nop 0
	v_addc_co_u32_e64 v129, s[4:5], 0, v129, s[4:5]
	global_load_dwordx4 v[140:143], v[128:129], off
	global_load_dwordx4 v[136:139], v[132:133], off offset:16
	s_nop 0
	global_load_dwordx4 v[128:131], v[132:133], off offset:528
	s_nop 0
	global_load_dwordx4 v[132:135], v[132:133], off offset:512
	v_cndmask_b32_e64 v199, 0, v161, s[2:3]
	v_cndmask_b32_e64 v224, v173, v175, s[2:3]
	v_lshl_add_u64 v[200:201], s[42:43], 0, v[224:225]
	v_lshlrev_b64 v[198:199], 10, v[198:199]
	v_lshl_add_u64 v[198:199], v[200:201], 0, v[198:199]
	v_lshl_add_u64 v[202:203], v[198:199], 0, v[196:197]
	v_cmp_gt_i32_e64 s[2:3], s82, v160
	v_add_u32_e32 v161, 0xffffc010, v160
	s_waitcnt vmcnt(7)
	v_pk_fma_f32 v[200:201], v[126:127], v[188:189], v[154:155] op_sel_hi:[1,0,1]
	v_pk_fma_f32 v[198:199], v[124:125], v[188:189], v[152:153] op_sel_hi:[1,0,1]
	s_mov_b32 s98, 0xff00ff
	s_mov_b32 s99, 0xff00ff
	s_mov_b32 s32, 0xffffe010
	s_mov_b32 s100, 0xffffdff0
	s_movk_i32 s101, 0x1ff0
	v_mov_b32_e32 v244, v198
	v_mov_b32_e32 v245, v199
	v_mov_b32_e32 v246, v200
	v_mov_b32_e32 v247, v201
	v_cndmask_b32_e64 v169, 0, v169, s[2:3]
	v_cndmask_b32_e64 v168, v161, v168, s[2:3]
	s_waitcnt vmcnt(6)
	v_pk_fma_f32 v[200:201], v[122:123], v[188:189], v[158:159] op_sel_hi:[1,0,1]
	v_pk_fma_f32 v[198:199], v[120:121], v[188:189], v[156:157] op_sel_hi:[1,0,1]
	s_nop 1
	v_mov_b32_dpp v248, v198 row_ror:8 row_mask:0xf bank_mask:0xf
	v_mov_b32_dpp v249, v199 row_ror:8 row_mask:0xf bank_mask:0xf
	v_mov_b32_dpp v250, v200 row_ror:8 row_mask:0xf bank_mask:0xf
	v_mov_b32_dpp v251, v201 row_ror:8 row_mask:0xf bank_mask:0xf
	v_cndmask_b32_e64 v198, v248, v244, s[98:99]
	v_cndmask_b32_e64 v199, v249, v245, s[98:99]
	v_cndmask_b32_e64 v200, v250, v246, s[98:99]
	v_cndmask_b32_e64 v201, v251, v247, s[98:99]
	v_cndmask_b32_e64 v244, v244, v248, s[98:99]
	v_cndmask_b32_e64 v245, v245, v249, s[98:99]
	v_cndmask_b32_e64 v246, v246, v250, s[98:99]
	v_cndmask_b32_e64 v247, v247, v251, s[98:99]
	v_cndmask_b32_e64 v250, 1, 0, s[98:99]
	v_cndmask_b32_e64 v251, 0, 1, s[98:99]
	v_mul_i32_i24_e32 v248, s32, v250
	v_sub_u32_e32 v249, 0, v250
	v_lshl_add_u64 v[202:203], v[202:203], 0, v[248:249]
	global_store_dwordx4 v[202:203], v[198:201], off
	v_lshl_add_u32 v248, v251, 5, s101
	v_mov_b32_e32 v249, 0
	v_lshl_add_u64 v[202:203], v[202:203], 0, v[248:249]
	global_store_dwordx4 v[202:203], v[244:247], off
	v_mul_i32_i24_e32 v248, s100, v251
	v_sub_u32_e32 v249, 0, v251
	v_lshl_add_u64 v[202:203], v[202:203], 0, v[248:249]
	v_cndmask_b32_e64 v224, v173, v175, s[2:3]
	v_lshlrev_b64 v[168:169], 10, v[168:169]
	s_waitcnt vmcnt(5)
;     template <int PN> DI void body(AccRef acc, const Unit& u, int wr, int wc, int fr, int fq) const {
;     ...
;                     float* lo = orow(out, l, row, PN == 8 ? O_PSK : O_PSV, PN == 8 ? O_SSK : O_SSV, 256);
; #pragma unroll
;                     for (int bj = 0; bj < 2; ++bj) {
;                         *(f32x4*)(lo + bj * 128 + cl) = (f32x4){v[bj][0], v[bj][1], v[bj][2], v[bj][3]};
;                         *(f32x4*)(lo + bj * 128 + cl + 4) = (f32x4){v[bj][4], v[bj][5], v[bj][6], v[bj][7]};
;                     }
	v_pk_fma_f32 v[200:201], v[118:119], v[188:189], v[150:151] op_sel_hi:[1,0,1]
	v_pk_fma_f32 v[198:199], v[116:117], v[188:189], v[148:149] op_sel_hi:[1,0,1]
	v_mov_b32_e32 v244, v198
	v_mov_b32_e32 v245, v199
	v_mov_b32_e32 v246, v200
	v_mov_b32_e32 v247, v201
	v_cmp_gt_i32_e64 s[2:3], s83, v160
	v_add_u32_e32 v161, 0xffffc020, v160
	v_pk_fma_f32 v[200:201], v[114:115], v[188:189], v[146:147] op_sel_hi:[1,0,1]
	v_pk_fma_f32 v[198:199], v[112:113], v[188:189], v[144:145] op_sel_hi:[1,0,1]
	v_lshl_add_u64 v[188:189], s[42:43], 0, v[224:225]
	v_lshl_add_u64 v[168:169], v[188:189], 0, v[168:169]
	s_nop 1
	v_mov_b32_dpp v248, v198 row_ror:8 row_mask:0xf bank_mask:0xf
	v_mov_b32_dpp v249, v199 row_ror:8 row_mask:0xf bank_mask:0xf
	v_mov_b32_dpp v250, v200 row_ror:8 row_mask:0xf bank_mask:0xf
	v_mov_b32_dpp v251, v201 row_ror:8 row_mask:0xf bank_mask:0xf
	v_cndmask_b32_e64 v198, v248, v244, s[98:99]
	v_cndmask_b32_e64 v199, v249, v245, s[98:99]
	v_cndmask_b32_e64 v200, v250, v246, s[98:99]
	v_cndmask_b32_e64 v201, v251, v247, s[98:99]
	v_cndmask_b32_e64 v244, v244, v248, s[98:99]
	v_cndmask_b32_e64 v245, v245, v249, s[98:99]
	v_cndmask_b32_e64 v246, v246, v250, s[98:99]
	v_cndmask_b32_e64 v247, v247, v251, s[98:99]
	v_cndmask_b32_e64 v250, 1, 0, s[98:99]
	v_cndmask_b32_e64 v251, 0, 1, s[98:99]
	v_mul_i32_i24_e32 v248, s32, v250
	v_sub_u32_e32 v249, 0, v250
	v_lshl_add_u64 v[202:203], v[202:203], 0, v[248:249]
	global_store_dwordx4 v[202:203], v[198:201], off offset:512
	v_lshl_add_u32 v248, v251, 5, s101
	v_mov_b32_e32 v249, 0
	v_lshl_add_u64 v[202:203], v[202:203], 0, v[248:249]
	global_store_dwordx4 v[202:203], v[244:247], off offset:512
	v_mul_i32_i24_e32 v248, s100, v251
	v_sub_u32_e32 v249, 0, v251
	v_lshl_add_u64 v[202:203], v[202:203], 0, v[248:249]
	v_lshl_add_u64 v[168:169], v[168:169], 0, v[196:197]
	v_cndmask_b32_e64 v165, 0, v165, s[2:3]
	v_pk_fma_f32 v[200:201], v[110:111], v[162:163], v[154:155] op_sel_hi:[1,0,1]
	v_pk_fma_f32 v[198:199], v[108:109], v[162:163], v[152:153] op_sel_hi:[1,0,1]
	v_mov_b32_e32 v244, v198
	v_mov_b32_e32 v245, v199
	v_mov_b32_e32 v246, v200
	v_mov_b32_e32 v247, v201
	v_cndmask_b32_e64 v164, v161, v164, s[2:3]
	v_cndmask_b32_e64 v224, v173, v175, s[2:3]
	v_pk_fma_f32 v[200:201], v[106:107], v[162:163], v[158:159] op_sel_hi:[1,0,1]
	v_pk_fma_f32 v[198:199], v[104:105], v[162:163], v[156:157] op_sel_hi:[1,0,1]
	s_nop 1
	v_mov_b32_dpp v248, v198 row_ror:8 row_mask:0xf bank_mask:0xf
	v_mov_b32_dpp v249, v199 row_ror:8 row_mask:0xf bank_mask:0xf
	v_mov_b32_dpp v250, v200 row_ror:8 row_mask:0xf bank_mask:0xf
	v_mov_b32_dpp v251, v201 row_ror:8 row_mask:0xf bank_mask:0xf
	v_cndmask_b32_e64 v198, v248, v244, s[98:99]
	v_cndmask_b32_e64 v199, v249, v245, s[98:99]
	v_cndmask_b32_e64 v200, v250, v246, s[98:99]
	v_cndmask_b32_e64 v201, v251, v247, s[98:99]
	v_cndmask_b32_e64 v244, v244, v248, s[98:99]
	v_cndmask_b32_e64 v245, v245, v249, s[98:99]
	v_cndmask_b32_e64 v246, v246, v250, s[98:99]
	v_cndmask_b32_e64 v247, v247, v251, s[98:99]
	v_cndmask_b32_e64 v250, 1, 0, s[98:99]
	v_cndmask_b32_e64 v251, 0, 1, s[98:99]
	v_mul_i32_i24_e32 v248, s32, v250
	v_sub_u32_e32 v249, 0, v250
	v_lshl_add_u64 v[168:169], v[168:169], 0, v[248:249]
	global_store_dwordx4 v[168:169], v[198:201], off
	v_lshl_add_u32 v248, v251, 5, s101
	v_mov_b32_e32 v249, 0
	v_lshl_add_u64 v[168:169], v[168:169], 0, v[248:249]
	global_store_dwordx4 v[168:169], v[244:247], off
	v_mul_i32_i24_e32 v248, s100, v251
	v_sub_u32_e32 v249, 0, v251
	v_lshl_add_u64 v[168:169], v[168:169], 0, v[248:249]
	v_lshlrev_b64 v[164:165], 10, v[164:165]
	v_cmp_gt_i32_e64 s[2:3], s92, v160
	v_pk_fma_f32 v[200:201], v[102:103], v[162:163], v[150:151] op_sel_hi:[1,0,1]
	v_pk_fma_f32 v[198:199], v[100:101], v[162:163], v[148:149] op_sel_hi:[1,0,1]
	v_mov_b32_e32 v244, v198
	v_mov_b32_e32 v245, v199
	v_mov_b32_e32 v246, v200
	v_mov_b32_e32 v247, v201
	v_add_u32_e32 v161, 0xffffc030, v160
	s_nop 0
	v_pk_fma_f32 v[200:201], v[98:99], v[162:163], v[146:147] op_sel_hi:[1,0,1]
	v_pk_fma_f32 v[198:199], v[96:97], v[162:163], v[144:145] op_sel_hi:[1,0,1]
	s_nop 1
	v_mov_b32_dpp v248, v198 row_ror:8 row_mask:0xf bank_mask:0xf
	v_mov_b32_dpp v249, v199 row_ror:8 row_mask:0xf bank_mask:0xf
	v_mov_b32_dpp v250, v200 row_ror:8 row_mask:0xf bank_mask:0xf
	v_mov_b32_dpp v251, v201 row_ror:8 row_mask:0xf bank_mask:0xf
	v_cndmask_b32_e64 v198, v248, v244, s[98:99]
	v_cndmask_b32_e64 v199, v249, v245, s[98:99]
	v_cndmask_b32_e64 v200, v250, v246, s[98:99]
	v_cndmask_b32_e64 v201, v251, v247, s[98:99]
	v_cndmask_b32_e64 v244, v244, v248, s[98:99]
	v_cndmask_b32_e64 v245, v245, v249, s[98:99]
	v_cndmask_b32_e64 v246, v246, v250, s[98:99]
	v_cndmask_b32_e64 v247, v247, v251, s[98:99]
	v_cndmask_b32_e64 v250, 1, 0, s[98:99]
	v_cndmask_b32_e64 v251, 0, 1, s[98:99]
	v_mul_i32_i24_e32 v248, s32, v250
	v_sub_u32_e32 v249, 0, v250
	v_lshl_add_u64 v[168:169], v[168:169], 0, v[248:249]
	global_store_dwordx4 v[168:169], v[198:201], off offset:512
	v_lshl_add_u32 v248, v251, 5, s101
	v_mov_b32_e32 v249, 0
	v_lshl_add_u64 v[168:169], v[168:169], 0, v[248:249]
	global_store_dwordx4 v[168:169], v[244:247], off offset:512
	v_mul_i32_i24_e32 v248, s100, v251
	v_sub_u32_e32 v249, 0, v251
	v_lshl_add_u64 v[168:169], v[168:169], 0, v[248:249]
	v_lshl_add_u64 v[168:169], s[42:43], 0, v[224:225]
	v_lshl_add_u64 v[164:165], v[168:169], 0, v[164:165]
	v_lshl_add_u64 v[164:165], v[164:165], 0, v[196:197]
	v_pk_fma_f32 v[200:201], v[94:95], v[170:171], v[154:155] op_sel_hi:[1,0,1]
	v_pk_fma_f32 v[198:199], v[92:93], v[170:171], v[152:153] op_sel_hi:[1,0,1]
	v_mov_b32_e32 v244, v198
	v_mov_b32_e32 v245, v199
;     template <int PN> DI void body(AccRef acc, const Unit& u, int wr, int wc, int fr, int fq) const {
;     ...
;                     float* lo = orow(out, l, row, PN == 8 ? O_PSK : O_PSV, PN == 8 ? O_SSK : O_SSV, 256);
; #pragma unroll
;                     for (int bj = 0; bj < 2; ++bj) {
;                         *(f32x4*)(lo + bj * 128 + cl) = (f32x4){v[bj][0], v[bj][1], v[bj][2], v[bj][3]};
;                         *(f32x4*)(lo + bj * 128 + cl + 4) = (f32x4){v[bj][4], v[bj][5], v[bj][6], v[bj][7]};
;                     }
	v_mov_b32_e32 v246, v200
	v_mov_b32_e32 v247, v201
	v_cndmask_b32_e64 v224, v173, v175, s[2:3]
	v_pk_fma_f32 v[154:155], v[78:79], v[174:175], v[154:155] op_sel_hi:[1,0,1]
	v_pk_fma_f32 v[200:201], v[90:91], v[170:171], v[158:159] op_sel_hi:[1,0,1]
	v_pk_fma_f32 v[198:199], v[88:89], v[170:171], v[156:157] op_sel_hi:[1,0,1]
	s_nop 1
	v_mov_b32_dpp v248, v198 row_ror:8 row_mask:0xf bank_mask:0xf
	v_mov_b32_dpp v249, v199 row_ror:8 row_mask:0xf bank_mask:0xf
	v_mov_b32_dpp v250, v200 row_ror:8 row_mask:0xf bank_mask:0xf
	v_mov_b32_dpp v251, v201 row_ror:8 row_mask:0xf bank_mask:0xf
	v_cndmask_b32_e64 v198, v248, v244, s[98:99]
	v_cndmask_b32_e64 v199, v249, v245, s[98:99]
	v_cndmask_b32_e64 v200, v250, v246, s[98:99]
	v_cndmask_b32_e64 v201, v251, v247, s[98:99]
	v_cndmask_b32_e64 v244, v244, v248, s[98:99]
	v_cndmask_b32_e64 v245, v245, v249, s[98:99]
	v_cndmask_b32_e64 v246, v246, v250, s[98:99]
	v_cndmask_b32_e64 v247, v247, v251, s[98:99]
	v_cndmask_b32_e64 v250, 1, 0, s[98:99]
	v_cndmask_b32_e64 v251, 0, 1, s[98:99]
	v_mul_i32_i24_e32 v248, s32, v250
	v_sub_u32_e32 v249, 0, v250
	v_lshl_add_u64 v[164:165], v[164:165], 0, v[248:249]
	global_store_dwordx4 v[164:165], v[198:201], off
	v_lshl_add_u32 v248, v251, 5, s101
	v_mov_b32_e32 v249, 0
	v_lshl_add_u64 v[164:165], v[164:165], 0, v[248:249]
	global_store_dwordx4 v[164:165], v[244:247], off
	v_mul_i32_i24_e32 v248, s100, v251
	v_sub_u32_e32 v249, 0, v251
	v_lshl_add_u64 v[164:165], v[164:165], 0, v[248:249]
	v_pk_fma_f32 v[152:153], v[76:77], v[174:175], v[152:153] op_sel_hi:[1,0,1]
	s_nop 0
	v_pk_fma_f32 v[200:201], v[86:87], v[170:171], v[150:151] op_sel_hi:[1,0,1]
	v_pk_fma_f32 v[198:199], v[84:85], v[170:171], v[148:149] op_sel_hi:[1,0,1]
	v_mov_b32_e32 v244, v198
	v_mov_b32_e32 v245, v199
	v_mov_b32_e32 v246, v200
	v_mov_b32_e32 v247, v201
	v_pk_fma_f32 v[150:151], v[70:71], v[174:175], v[150:151] op_sel_hi:[1,0,1]
	v_pk_fma_f32 v[148:149], v[68:69], v[174:175], v[148:149] op_sel_hi:[1,0,1]
	v_pk_fma_f32 v[200:201], v[82:83], v[170:171], v[146:147] op_sel_hi:[1,0,1]
	v_pk_fma_f32 v[198:199], v[80:81], v[170:171], v[144:145] op_sel_hi:[1,0,1]
	s_nop 1
	v_mov_b32_dpp v248, v198 row_ror:8 row_mask:0xf bank_mask:0xf
	v_mov_b32_dpp v249, v199 row_ror:8 row_mask:0xf bank_mask:0xf
	v_mov_b32_dpp v250, v200 row_ror:8 row_mask:0xf bank_mask:0xf
	v_mov_b32_dpp v251, v201 row_ror:8 row_mask:0xf bank_mask:0xf
	v_cndmask_b32_e64 v198, v248, v244, s[98:99]
	v_cndmask_b32_e64 v199, v249, v245, s[98:99]
	v_cndmask_b32_e64 v200, v250, v246, s[98:99]
	v_cndmask_b32_e64 v201, v251, v247, s[98:99]
	v_cndmask_b32_e64 v244, v244, v248, s[98:99]
	v_cndmask_b32_e64 v245, v245, v249, s[98:99]
	v_cndmask_b32_e64 v246, v246, v250, s[98:99]
	v_cndmask_b32_e64 v247, v247, v251, s[98:99]
	v_cndmask_b32_e64 v250, 1, 0, s[98:99]
	v_cndmask_b32_e64 v251, 0, 1, s[98:99]
	v_mul_i32_i24_e32 v248, s32, v250
	v_sub_u32_e32 v249, 0, v250
	v_lshl_add_u64 v[164:165], v[164:165], 0, v[248:249]
	global_store_dwordx4 v[164:165], v[198:201], off offset:512
	v_lshl_add_u32 v248, v251, 5, s101
	v_mov_b32_e32 v249, 0
	v_lshl_add_u64 v[164:165], v[164:165], 0, v[248:249]
	global_store_dwordx4 v[164:165], v[244:247], off offset:512
	v_mul_i32_i24_e32 v248, s100, v251
	v_sub_u32_e32 v249, 0, v251
	v_lshl_add_u64 v[164:165], v[164:165], 0, v[248:249]
	v_cndmask_b32_e64 v165, 0, v167, s[2:3]
	v_cndmask_b32_e64 v164, v161, v166, s[2:3]
	v_lshl_add_u64 v[166:167], s[42:43], 0, v[224:225]
	v_lshlrev_b64 v[164:165], 10, v[164:165]
	v_lshl_add_u64 v[164:165], v[166:167], 0, v[164:165]
	v_lshl_add_u64 v[164:165], v[164:165], 0, v[196:197]
	v_pk_fma_f32 v[146:147], v[66:67], v[174:175], v[146:147] op_sel_hi:[1,0,1]
	v_pk_fma_f32 v[144:145], v[64:65], v[174:175], v[144:145] op_sel_hi:[1,0,1]
	global_store_dwordx4 v[164:165], v[144:147], off offset:528
	v_cndmask_b32_e32 v224, v173, v175, vcc
	global_store_dwordx4 v[164:165], v[152:155], off
	v_ashrrev_i32_e32 v144, 31, v163
	v_cndmask_b32_e32 v145, 0, v144, vcc
	v_cndmask_b32_e32 v144, v171, v163, vcc
	v_lshl_add_u64 v[146:147], s[42:43], 0, v[224:225]
	v_lshlrev_b64 v[144:145], 10, v[144:145]
	v_lshl_add_u64 v[144:145], v[146:147], 0, v[144:145]
	v_pk_fma_f32 v[154:155], v[74:75], v[174:175], v[158:159] op_sel_hi:[1,0,1]
	v_pk_fma_f32 v[152:153], v[72:73], v[174:175], v[156:157] op_sel_hi:[1,0,1]
	global_store_dwordx4 v[164:165], v[148:151], off offset:512
	s_waitcnt vmcnt(17)
	v_pk_fma_f32 v[146:147], v[62:63], v[190:191], v[142:143] op_sel_hi:[1,0,1]
	global_store_dwordx4 v[164:165], v[152:155], off offset:16
	v_lshl_add_u64 v[148:149], v[144:145], 0, v[196:197]
	v_pk_fma_f32 v[144:145], v[60:61], v[190:191], v[140:141] op_sel_hi:[1,0,1]
	v_mov_b32_e32 v244, v144
	v_mov_b32_e32 v245, v145
	v_mov_b32_e32 v246, v146
	v_mov_b32_e32 v247, v147
	v_cmp_gt_i32_e32 vcc, s82, v163
	s_waitcnt vmcnt(18)
	v_pk_fma_f32 v[146:147], v[58:59], v[190:191], v[138:139] op_sel_hi:[1,0,1]
	v_pk_fma_f32 v[144:145], v[56:57], v[190:191], v[136:137] op_sel_hi:[1,0,1]
	s_nop 1
	v_mov_b32_dpp v248, v144 row_ror:8 row_mask:0xf bank_mask:0xf
	v_mov_b32_dpp v249, v145 row_ror:8 row_mask:0xf bank_mask:0xf
	v_mov_b32_dpp v250, v146 row_ror:8 row_mask:0xf bank_mask:0xf
	v_mov_b32_dpp v251, v147 row_ror:8 row_mask:0xf bank_mask:0xf
	v_cndmask_b32_e64 v144, v248, v244, s[98:99]
	v_cndmask_b32_e64 v145, v249, v245, s[98:99]
	v_cndmask_b32_e64 v146, v250, v246, s[98:99]
	v_cndmask_b32_e64 v147, v251, v247, s[98:99]
	v_cndmask_b32_e64 v244, v244, v248, s[98:99]
	v_cndmask_b32_e64 v245, v245, v249, s[98:99]
	v_cndmask_b32_e64 v246, v246, v250, s[98:99]
	v_cndmask_b32_e64 v247, v247, v251, s[98:99]
	v_cndmask_b32_e64 v250, 1, 0, s[98:99]
	v_cndmask_b32_e64 v251, 0, 1, s[98:99]
	v_mul_i32_i24_e32 v248, s32, v250
	v_sub_u32_e32 v249, 0, v250
	v_lshl_add_u64 v[148:149], v[148:149], 0, v[248:249]
	global_store_dwordx4 v[148:149], v[144:147], off
	v_lshl_add_u32 v248, v251, 5, s101
	v_mov_b32_e32 v249, 0
	v_lshl_add_u64 v[148:149], v[148:149], 0, v[248:249]
	global_store_dwordx4 v[148:149], v[244:247], off
	v_mul_i32_i24_e32 v248, s100, v251
	v_sub_u32_e32 v249, 0, v251
	v_lshl_add_u64 v[148:149], v[148:149], 0, v[248:249]
	v_cndmask_b32_e32 v224, v173, v175, vcc
	s_waitcnt vmcnt(17)
;     template <int PN> DI void body(AccRef acc, const Unit& u, int wr, int wc, int fr, int fq) const {
;     ...
;                     float* lo = orow(out, l, row, PN == 8 ? O_PSK : O_PSV, PN == 8 ? O_SSK : O_SSV, 256);
; #pragma unroll
;                     for (int bj = 0; bj < 2; ++bj) {
;                         *(f32x4*)(lo + bj * 128 + cl) = (f32x4){v[bj][0], v[bj][1], v[bj][2], v[bj][3]};
;                         *(f32x4*)(lo + bj * 128 + cl + 4) = (f32x4){v[bj][4], v[bj][5], v[bj][6], v[bj][7]};
;                     }
	v_pk_fma_f32 v[146:147], v[54:55], v[190:191], v[134:135] op_sel_hi:[1,0,1]
	v_pk_fma_f32 v[144:145], v[52:53], v[190:191], v[132:133] op_sel_hi:[1,0,1]
	v_mov_b32_e32 v244, v144
	v_mov_b32_e32 v245, v145
	v_mov_b32_e32 v246, v146
	v_mov_b32_e32 v247, v147
	s_nop 1
	v_pk_fma_f32 v[146:147], v[50:51], v[190:191], v[130:131] op_sel_hi:[1,0,1]
	v_pk_fma_f32 v[144:145], v[48:49], v[190:191], v[128:129] op_sel_hi:[1,0,1]
	s_nop 1
	v_mov_b32_dpp v248, v144 row_ror:8 row_mask:0xf bank_mask:0xf
	v_mov_b32_dpp v249, v145 row_ror:8 row_mask:0xf bank_mask:0xf
	v_mov_b32_dpp v250, v146 row_ror:8 row_mask:0xf bank_mask:0xf
	v_mov_b32_dpp v251, v147 row_ror:8 row_mask:0xf bank_mask:0xf
	v_cndmask_b32_e64 v144, v248, v244, s[98:99]
	v_cndmask_b32_e64 v145, v249, v245, s[98:99]
	v_cndmask_b32_e64 v146, v250, v246, s[98:99]
	v_cndmask_b32_e64 v147, v251, v247, s[98:99]
	v_cndmask_b32_e64 v244, v244, v248, s[98:99]
	v_cndmask_b32_e64 v245, v245, v249, s[98:99]
	v_cndmask_b32_e64 v246, v246, v250, s[98:99]
	v_cndmask_b32_e64 v247, v247, v251, s[98:99]
	v_cndmask_b32_e64 v250, 1, 0, s[98:99]
	v_cndmask_b32_e64 v251, 0, 1, s[98:99]
	v_mul_i32_i24_e32 v248, s32, v250
	v_sub_u32_e32 v249, 0, v250
	v_lshl_add_u64 v[148:149], v[148:149], 0, v[248:249]
	global_store_dwordx4 v[148:149], v[144:147], off offset:512
	v_lshl_add_u32 v248, v251, 5, s101
	v_mov_b32_e32 v249, 0
	v_lshl_add_u64 v[148:149], v[148:149], 0, v[248:249]
	global_store_dwordx4 v[148:149], v[244:247], off offset:512
	v_mul_i32_i24_e32 v248, s100, v251
	v_sub_u32_e32 v249, 0, v251
	v_lshl_add_u64 v[148:149], v[148:149], 0, v[248:249]
	s_nop 1
	v_add_u32_e32 v146, 0x90, v160
	v_add_u32_e32 v144, 0xffffc090, v160
	v_ashrrev_i32_e32 v145, 31, v146
	v_cndmask_b32_e32 v145, 0, v145, vcc
	v_cndmask_b32_e32 v144, v144, v146, vcc
	v_lshl_add_u64 v[146:147], s[42:43], 0, v[224:225]
	v_lshlrev_b64 v[144:145], 10, v[144:145]
	v_lshl_add_u64 v[144:145], v[146:147], 0, v[144:145]
	v_lshl_add_u64 v[148:149], v[144:145], 0, v[196:197]
	v_pk_fma_f32 v[146:147], v[46:47], v[172:173], v[142:143] op_sel_hi:[1,0,1]
	v_pk_fma_f32 v[144:145], v[44:45], v[172:173], v[140:141] op_sel_hi:[1,0,1]
	v_mov_b32_e32 v244, v144
	v_mov_b32_e32 v245, v145
	v_mov_b32_e32 v246, v146
	v_mov_b32_e32 v247, v147
	v_cmp_gt_i32_e32 vcc, s83, v163
	s_nop 0
	v_pk_fma_f32 v[146:147], v[42:43], v[172:173], v[138:139] op_sel_hi:[1,0,1]
	v_pk_fma_f32 v[144:145], v[40:41], v[172:173], v[136:137] op_sel_hi:[1,0,1]
	s_nop 1
	v_mov_b32_dpp v248, v144 row_ror:8 row_mask:0xf bank_mask:0xf
	v_mov_b32_dpp v249, v145 row_ror:8 row_mask:0xf bank_mask:0xf
	v_mov_b32_dpp v250, v146 row_ror:8 row_mask:0xf bank_mask:0xf
	v_mov_b32_dpp v251, v147 row_ror:8 row_mask:0xf bank_mask:0xf
	v_cndmask_b32_e64 v144, v248, v244, s[98:99]
	v_cndmask_b32_e64 v145, v249, v245, s[98:99]
	v_cndmask_b32_e64 v146, v250, v246, s[98:99]
	v_cndmask_b32_e64 v147, v251, v247, s[98:99]
	v_cndmask_b32_e64 v244, v244, v248, s[98:99]
	v_cndmask_b32_e64 v245, v245, v249, s[98:99]
	v_cndmask_b32_e64 v246, v246, v250, s[98:99]
	v_cndmask_b32_e64 v247, v247, v251, s[98:99]
	v_cndmask_b32_e64 v250, 1, 0, s[98:99]
	v_cndmask_b32_e64 v251, 0, 1, s[98:99]
	v_mul_i32_i24_e32 v248, s32, v250
	v_sub_u32_e32 v249, 0, v250
	v_lshl_add_u64 v[148:149], v[148:149], 0, v[248:249]
	global_store_dwordx4 v[148:149], v[144:147], off
	v_lshl_add_u32 v248, v251, 5, s101
	v_mov_b32_e32 v249, 0
	v_lshl_add_u64 v[148:149], v[148:149], 0, v[248:249]
	global_store_dwordx4 v[148:149], v[244:247], off
	v_mul_i32_i24_e32 v248, s100, v251
	v_sub_u32_e32 v249, 0, v251
	v_lshl_add_u64 v[148:149], v[148:149], 0, v[248:249]
	v_cndmask_b32_e32 v224, v173, v175, vcc
	s_nop 0
	v_pk_fma_f32 v[146:147], v[38:39], v[172:173], v[134:135] op_sel_hi:[1,0,1]
	v_pk_fma_f32 v[144:145], v[36:37], v[172:173], v[132:133] op_sel_hi:[1,0,1]
	v_mov_b32_e32 v244, v144
	v_mov_b32_e32 v245, v145
	v_mov_b32_e32 v246, v146
	v_mov_b32_e32 v247, v147
	s_nop 1
	v_pk_fma_f32 v[146:147], v[30:31], v[172:173], v[130:131] op_sel_hi:[1,0,1]
	v_pk_fma_f32 v[144:145], v[28:29], v[172:173], v[128:129] op_sel_hi:[1,0,1]
	s_nop 1
	v_mov_b32_dpp v248, v144 row_ror:8 row_mask:0xf bank_mask:0xf
	v_mov_b32_dpp v249, v145 row_ror:8 row_mask:0xf bank_mask:0xf
	v_mov_b32_dpp v250, v146 row_ror:8 row_mask:0xf bank_mask:0xf
	v_mov_b32_dpp v251, v147 row_ror:8 row_mask:0xf bank_mask:0xf
	v_cndmask_b32_e64 v144, v248, v244, s[98:99]
	v_cndmask_b32_e64 v145, v249, v245, s[98:99]
	v_cndmask_b32_e64 v146, v250, v246, s[98:99]
	v_cndmask_b32_e64 v147, v251, v247, s[98:99]
	v_cndmask_b32_e64 v244, v244, v248, s[98:99]
	v_cndmask_b32_e64 v245, v245, v249, s[98:99]
	v_cndmask_b32_e64 v246, v246, v250, s[98:99]
	v_cndmask_b32_e64 v247, v247, v251, s[98:99]
	v_cndmask_b32_e64 v250, 1, 0, s[98:99]
	v_cndmask_b32_e64 v251, 0, 1, s[98:99]
	v_mul_i32_i24_e32 v248, s32, v250
	v_sub_u32_e32 v249, 0, v250
	v_lshl_add_u64 v[148:149], v[148:149], 0, v[248:249]
	global_store_dwordx4 v[148:149], v[144:147], off offset:512
	v_lshl_add_u32 v248, v251, 5, s101
	v_mov_b32_e32 v249, 0
	v_lshl_add_u64 v[148:149], v[148:149], 0, v[248:249]
	global_store_dwordx4 v[148:149], v[244:247], off offset:512
	v_mul_i32_i24_e32 v248, s100, v251
	v_sub_u32_e32 v249, 0, v251
	v_lshl_add_u64 v[148:149], v[148:149], 0, v[248:249]
	s_nop 1
	v_add_u32_e32 v146, 0xa0, v160
	v_add_u32_e32 v144, 0xffffc0a0, v160
	v_ashrrev_i32_e32 v145, 31, v146
	v_cndmask_b32_e32 v145, 0, v145, vcc
	v_cndmask_b32_e32 v144, v144, v146, vcc
	v_lshl_add_u64 v[146:147], s[42:43], 0, v[224:225]
	v_lshlrev_b64 v[144:145], 10, v[144:145]
	v_lshl_add_u64 v[144:145], v[146:147], 0, v[144:145]
	v_lshl_add_u64 v[148:149], v[144:145], 0, v[196:197]
;     template <int PN> DI void body(AccRef acc, const Unit& u, int wr, int wc, int fr, int fq) const {
;     ...
;                     float* lo = orow(out, l, row, PN == 8 ? O_PSK : O_PSV, PN == 8 ? O_SSK : O_SSV, 256);
; #pragma unroll
;                     for (int bj = 0; bj < 2; ++bj) {
;                         *(f32x4*)(lo + bj * 128 + cl) = (f32x4){v[bj][0], v[bj][1], v[bj][2], v[bj][3]};
;                         *(f32x4*)(lo + bj * 128 + cl + 4) = (f32x4){v[bj][4], v[bj][5], v[bj][6], v[bj][7]};
;                     }
	v_pk_fma_f32 v[146:147], v[34:35], v[192:193], v[142:143] op_sel_hi:[1,0,1]
	v_pk_fma_f32 v[144:145], v[32:33], v[192:193], v[140:141] op_sel_hi:[1,0,1]
	v_mov_b32_e32 v244, v144
	v_mov_b32_e32 v245, v145
	v_mov_b32_e32 v246, v146
	v_mov_b32_e32 v247, v147
	v_cmp_gt_i32_e32 vcc, s92, v163
	v_pk_fma_f32 v[142:143], v[14:15], v[194:195], v[142:143] op_sel_hi:[1,0,1]
	v_pk_fma_f32 v[146:147], v[26:27], v[192:193], v[138:139] op_sel_hi:[1,0,1]
	v_pk_fma_f32 v[144:145], v[24:25], v[192:193], v[136:137] op_sel_hi:[1,0,1]
	s_nop 1
	v_mov_b32_dpp v248, v144 row_ror:8 row_mask:0xf bank_mask:0xf
	v_mov_b32_dpp v249, v145 row_ror:8 row_mask:0xf bank_mask:0xf
	v_mov_b32_dpp v250, v146 row_ror:8 row_mask:0xf bank_mask:0xf
	v_mov_b32_dpp v251, v147 row_ror:8 row_mask:0xf bank_mask:0xf
	v_cndmask_b32_e64 v144, v248, v244, s[98:99]
	v_cndmask_b32_e64 v145, v249, v245, s[98:99]
	v_cndmask_b32_e64 v146, v250, v246, s[98:99]
	v_cndmask_b32_e64 v147, v251, v247, s[98:99]
	v_cndmask_b32_e64 v244, v244, v248, s[98:99]
	v_cndmask_b32_e64 v245, v245, v249, s[98:99]
	v_cndmask_b32_e64 v246, v246, v250, s[98:99]
	v_cndmask_b32_e64 v247, v247, v251, s[98:99]
	v_cndmask_b32_e64 v250, 1, 0, s[98:99]
	v_cndmask_b32_e64 v251, 0, 1, s[98:99]
	v_mul_i32_i24_e32 v248, s32, v250
	v_sub_u32_e32 v249, 0, v250
	v_lshl_add_u64 v[148:149], v[148:149], 0, v[248:249]
	global_store_dwordx4 v[148:149], v[144:147], off
	v_lshl_add_u32 v248, v251, 5, s101
	v_mov_b32_e32 v249, 0
	v_lshl_add_u64 v[148:149], v[148:149], 0, v[248:249]
	global_store_dwordx4 v[148:149], v[244:247], off
	v_mul_i32_i24_e32 v248, s100, v251
	v_sub_u32_e32 v249, 0, v251
	v_lshl_add_u64 v[148:149], v[148:149], 0, v[248:249]
	v_cndmask_b32_e32 v224, v173, v175, vcc
	v_pk_fma_f32 v[140:141], v[12:13], v[194:195], v[140:141] op_sel_hi:[1,0,1]
	v_pk_fma_f32 v[146:147], v[22:23], v[192:193], v[134:135] op_sel_hi:[1,0,1]
	v_pk_fma_f32 v[144:145], v[20:21], v[192:193], v[132:133] op_sel_hi:[1,0,1]
	v_mov_b32_e32 v244, v144
	v_mov_b32_e32 v245, v145
	v_mov_b32_e32 v246, v146
	v_mov_b32_e32 v247, v147
	v_pk_fma_f32 v[138:139], v[10:11], v[194:195], v[138:139] op_sel_hi:[1,0,1]
	v_pk_fma_f32 v[136:137], v[8:9], v[194:195], v[136:137] op_sel_hi:[1,0,1]
	v_pk_fma_f32 v[146:147], v[18:19], v[192:193], v[130:131] op_sel_hi:[1,0,1]
	v_pk_fma_f32 v[144:145], v[16:17], v[192:193], v[128:129] op_sel_hi:[1,0,1]
	s_nop 1
	v_mov_b32_dpp v248, v144 row_ror:8 row_mask:0xf bank_mask:0xf
	v_mov_b32_dpp v249, v145 row_ror:8 row_mask:0xf bank_mask:0xf
	v_mov_b32_dpp v250, v146 row_ror:8 row_mask:0xf bank_mask:0xf
	v_mov_b32_dpp v251, v147 row_ror:8 row_mask:0xf bank_mask:0xf
	v_cndmask_b32_e64 v144, v248, v244, s[98:99]
	v_cndmask_b32_e64 v145, v249, v245, s[98:99]
	v_cndmask_b32_e64 v146, v250, v246, s[98:99]
	v_cndmask_b32_e64 v147, v251, v247, s[98:99]
	v_cndmask_b32_e64 v244, v244, v248, s[98:99]
	v_cndmask_b32_e64 v245, v245, v249, s[98:99]
	v_cndmask_b32_e64 v246, v246, v250, s[98:99]
	v_cndmask_b32_e64 v247, v247, v251, s[98:99]
	v_cndmask_b32_e64 v250, 1, 0, s[98:99]
	v_cndmask_b32_e64 v251, 0, 1, s[98:99]
	v_mul_i32_i24_e32 v248, s32, v250
	v_sub_u32_e32 v249, 0, v250
	v_lshl_add_u64 v[148:149], v[148:149], 0, v[248:249]
	global_store_dwordx4 v[148:149], v[144:147], off offset:512
	v_lshl_add_u32 v248, v251, 5, s101
	v_mov_b32_e32 v249, 0
	v_lshl_add_u64 v[148:149], v[148:149], 0, v[248:249]
	global_store_dwordx4 v[148:149], v[244:247], off offset:512
	v_mul_i32_i24_e32 v248, s100, v251
	v_sub_u32_e32 v249, 0, v251
	v_lshl_add_u64 v[148:149], v[148:149], 0, v[248:249]
	v_pk_fma_f32 v[134:135], v[6:7], v[194:195], v[134:135] op_sel_hi:[1,0,1]
	v_pk_fma_f32 v[132:133], v[4:5], v[194:195], v[132:133] op_sel_hi:[1,0,1]
	v_add_u32_e32 v146, 0xb0, v160
	v_add_u32_e32 v144, 0xffffc0b0, v160
	v_ashrrev_i32_e32 v145, 31, v146
	v_cndmask_b32_e32 v145, 0, v145, vcc
	v_cndmask_b32_e32 v144, v144, v146, vcc
	v_lshl_add_u64 v[146:147], s[42:43], 0, v[224:225]
	v_lshlrev_b64 v[144:145], 10, v[144:145]
	v_lshl_add_u64 v[144:145], v[146:147], 0, v[144:145]
	v_lshl_add_u64 v[144:145], v[144:145], 0, v[196:197]
	v_pk_fma_f32 v[130:131], v[2:3], v[194:195], v[130:131] op_sel_hi:[1,0,1]
	v_pk_fma_f32 v[128:129], v[0:1], v[194:195], v[128:129] op_sel_hi:[1,0,1]
	v_mov_b32_e32 v244, v140
	v_mov_b32_e32 v245, v141
	v_mov_b32_e32 v246, v142
	v_mov_b32_e32 v247, v143
	s_nop 1
	v_mov_b32_dpp v248, v136 row_ror:8 row_mask:0xf bank_mask:0xf
	v_mov_b32_dpp v249, v137 row_ror:8 row_mask:0xf bank_mask:0xf
	v_mov_b32_dpp v250, v138 row_ror:8 row_mask:0xf bank_mask:0xf
	v_mov_b32_dpp v251, v139 row_ror:8 row_mask:0xf bank_mask:0xf
	v_cndmask_b32_e64 v136, v248, v244, s[98:99]
	v_cndmask_b32_e64 v137, v249, v245, s[98:99]
	v_cndmask_b32_e64 v138, v250, v246, s[98:99]
	v_cndmask_b32_e64 v139, v251, v247, s[98:99]
	v_cndmask_b32_e64 v244, v244, v248, s[98:99]
	v_cndmask_b32_e64 v245, v245, v249, s[98:99]
	v_cndmask_b32_e64 v246, v246, v250, s[98:99]
	v_cndmask_b32_e64 v247, v247, v251, s[98:99]
	v_cndmask_b32_e64 v250, 1, 0, s[98:99]
	v_cndmask_b32_e64 v251, 0, 1, s[98:99]
	v_mul_i32_i24_e32 v248, s32, v250
	v_sub_u32_e32 v249, 0, v250
	v_lshl_add_u64 v[144:145], v[144:145], 0, v[248:249]
	global_store_dwordx4 v[144:145], v[136:139], off
	v_lshl_add_u32 v248, v251, 5, s101
	v_mov_b32_e32 v249, 0
	v_lshl_add_u64 v[144:145], v[144:145], 0, v[248:249]
	global_store_dwordx4 v[144:145], v[244:247], off
	v_mul_i32_i24_e32 v248, s100, v251
	v_sub_u32_e32 v249, 0, v251
	v_lshl_add_u64 v[144:145], v[144:145], 0, v[248:249]
	v_mov_b32_e32 v244, v132
	v_mov_b32_e32 v245, v133
	v_mov_b32_e32 v246, v134
	v_mov_b32_e32 v247, v135
	s_nop 1
	v_mov_b32_dpp v248, v128 row_ror:8 row_mask:0xf bank_mask:0xf
	v_mov_b32_dpp v249, v129 row_ror:8 row_mask:0xf bank_mask:0xf
	v_mov_b32_dpp v250, v130 row_ror:8 row_mask:0xf bank_mask:0xf
	v_mov_b32_dpp v251, v131 row_ror:8 row_mask:0xf bank_mask:0xf
	v_cndmask_b32_e64 v128, v248, v244, s[98:99]
	v_cndmask_b32_e64 v129, v249, v245, s[98:99]
	v_cndmask_b32_e64 v130, v250, v246, s[98:99]
	v_cndmask_b32_e64 v131, v251, v247, s[98:99]
	v_cndmask_b32_e64 v244, v244, v248, s[98:99]
	v_cndmask_b32_e64 v245, v245, v249, s[98:99]
	v_cndmask_b32_e64 v246, v246, v250, s[98:99]
	v_cndmask_b32_e64 v247, v247, v251, s[98:99]
	v_cndmask_b32_e64 v250, 1, 0, s[98:99]
	v_cndmask_b32_e64 v251, 0, 1, s[98:99]
	v_mul_i32_i24_e32 v248, s32, v250
	v_sub_u32_e32 v249, 0, v250
	v_lshl_add_u64 v[144:145], v[144:145], 0, v[248:249]
	global_store_dwordx4 v[144:145], v[128:131], off offset:512
	v_lshl_add_u32 v248, v251, 5, s101
	v_mov_b32_e32 v249, 0
	v_lshl_add_u64 v[144:145], v[144:145], 0, v[248:249]
	global_store_dwordx4 v[144:145], v[244:247], off offset:512
	v_mul_i32_i24_e32 v248, s100, v251
	v_sub_u32_e32 v249, 0, v251
	v_lshl_add_u64 v[144:145], v[144:145], 0, v[248:249]

; DI float sum16(const float* p) { const f32x4* q = (const f32x4*)p; f32x4 a = q[0], b = q[1], c = q[2], d = q[3]; f32x4 s = (a + b) + (c + d); return (s[0] + s[1]) + (s[2] + s[3]); }
;     template <int PN> DI void body(AccRef acc, const Unit& u, int wr, int wc, int fr, int fq) const {
;     ...
;         for (int ai = 0; ai < 2; ++ai) {
;             const int rb_ = u.pm * 256 + ai * 128 + wr * 64 + fr;
; #pragma unroll
;             for (int m = 0; m < 4; ++m) rinvh[ai][m] = rsqrtf(sum16(ssq + (size_t)(rb_ + 16 * m + zdep) * 16) * (1.f / 1024.f) + EPS);
;             asm volatile("v_mov_b32 %0, 0" : "=v"(zdep) : "v"(rinvh[ai][0]), "v"(rinvh[ai][1]), "v"(rinvh[ai][2]), "v"(rinvh[ai][3]));
;         }
; #pragma unroll
;         for (int ai = 0; ai < 2; ++ai) {
;             const int rb_ = u.pm * 256 + ai * 128 + wr * 64 + fr;
;             int mb_, p_, k_; row_info(rb_, mb_, p_, k_);
; #pragma unroll
;             for (int bj = 0; bj < 2; ++bj)
; #pragma unroll
;                 for (int n = 0; n < 2; ++n) cvh[ai][bj][n] = *(const f32x4*)(cv + (size_t)(mb_ + zdep) * NIN + PN * 256 + bj * 128 + cl + 4 * n);
;         }
;     DI void operator()(AccRef acc, const Unit& u, int wr, int wc, int fr, int fq) const {
;         switch (u.pn) {
;             case 0: body<0>(acc, u, wr, wc, fr, fq); break;
;             case 1: body<1>(acc, u, wr, wc, fr, fq); break;
;             case 2: body<2>(acc, u, wr, wc, fr, fq); break;
;             case 3: body<3>(acc, u, wr, wc, fr, fq); break;
;             case 4: body<4>(acc, u, wr, wc, fr, fq); break;
;             case 5: body<5>(acc, u, wr, wc, fr, fq); break;
;             case 6: body<6>(acc, u, wr, wc, fr, fq); break;
;             case 7: body<7>(acc, u, wr, wc, fr, fq); break;
;             case 8: body<8>(acc, u, wr, wc, fr, fq); break;
;             default: body<9>(acc, u, wr, wc, fr, fq); break;
;         }
.LBB0_1709:
	v_readlane_b32 s4, v253, 32
	v_mbcnt_lo_u32_b32 v128, -1, 0
	v_mbcnt_hi_u32_b32 v128, -1, v128
	s_mov_b32 s54, s39
	v_and_b32_e32 v214, 15, v128
	v_bfe_u32 v213, v128, 4, 2
	s_mov_b32 s43, s29
	s_lshl_b32 s22, s43, 6
	s_lshl_b32 s23, s34, 8
	s_add_i32 s22, s22, s23
	v_add_u32_e32 v244, s22, v214
	v_lshlrev_b32_e32 v244, 6, v244
	v_lshl_add_u32 v244, v213, 4, v244
	global_load_dwordx4 v[228:231], v244, s[70:71]
	global_load_dwordx4 v[232:235], v244, s[70:71] offset:1024
	global_load_dwordx4 v[236:239], v244, s[70:71] offset:2048
	global_load_dwordx4 v[240:243], v244, s[70:71] offset:3072
	v_add_u32_e32 v244, 0x2000, v244
	global_load_dwordx4 v[216:219], v244, s[70:71]
	global_load_dwordx4 v[220:223], v244, s[70:71] offset:1024
	global_load_dwordx4 v[142:145], v244, s[70:71] offset:2048
	global_load_dwordx4 v[146:149], v244, s[70:71] offset:3072
	v_mov_b32_e32 v245, 0x3a800000
	s_waitcnt vmcnt(4)
	v_pk_add_f32 v[228:229], v[228:229], v[230:231]
	v_pk_add_f32 v[232:233], v[232:233], v[234:235]
	v_pk_add_f32 v[236:237], v[236:237], v[238:239]
	v_pk_add_f32 v[240:241], v[240:241], v[242:243]
	v_add_f32_e32 v228, v228, v229
	v_add_f32_e32 v232, v232, v233
	v_add_f32_e32 v236, v236, v237
	v_add_f32_e32 v240, v240, v241
	v_mov_b32_e32 v229, v228
	v_mov_b32_e32 v233, v232
	v_mov_b32_e32 v237, v236
	v_mov_b32_e32 v241, v240
	s_waitcnt vmcnt(0)
	v_pk_add_f32 v[216:217], v[216:217], v[218:219]
	v_pk_add_f32 v[220:221], v[220:221], v[222:223]
	v_pk_add_f32 v[142:143], v[142:143], v[144:145]
	v_pk_add_f32 v[146:147], v[146:147], v[148:149]
	v_add_f32_e32 v216, v216, v217
	v_add_f32_e32 v220, v220, v221
	v_add_f32_e32 v142, v142, v143
	v_add_f32_e32 v146, v146, v147
	v_mov_b32_e32 v217, v216
	v_mov_b32_e32 v221, v220
	v_mov_b32_e32 v143, v142
	v_mov_b32_e32 v147, v146
	s_nop 1
	v_permlane32_swap_b32_e32 v228, v229
	v_permlane32_swap_b32_e32 v232, v233
	v_permlane32_swap_b32_e32 v236, v237
	v_permlane32_swap_b32_e32 v240, v241
	v_permlane32_swap_b32_e32 v216, v217
	v_permlane32_swap_b32_e32 v220, v221
	v_permlane32_swap_b32_e32 v142, v143
	v_permlane32_swap_b32_e32 v146, v147
	v_add_f32_e32 v228, v228, v229
	v_add_f32_e32 v232, v232, v233
	v_add_f32_e32 v236, v236, v237
	v_add_f32_e32 v240, v240, v241
	v_add_f32_e32 v216, v216, v217
	v_add_f32_e32 v220, v220, v221
	v_add_f32_e32 v142, v142, v143
	v_add_f32_e32 v146, v146, v147
	v_mov_b32_e32 v229, v228
	v_mov_b32_e32 v233, v232
	v_mov_b32_e32 v237, v236
	v_mov_b32_e32 v241, v240
	v_mov_b32_e32 v217, v216
	v_mov_b32_e32 v221, v220
	v_mov_b32_e32 v143, v142
	v_mov_b32_e32 v147, v146
	s_nop 1
	v_permlane16_swap_b32_e32 v228, v229
	v_permlane16_swap_b32_e32 v232, v233
	v_permlane16_swap_b32_e32 v236, v237
	v_permlane16_swap_b32_e32 v240, v241
	v_permlane16_swap_b32_e32 v216, v217
	v_permlane16_swap_b32_e32 v220, v221
	v_permlane16_swap_b32_e32 v142, v143
	v_permlane16_swap_b32_e32 v146, v147
	v_add_f32_e32 v228, v228, v229
	v_add_f32_e32 v232, v232, v233
	v_add_f32_e32 v236, v236, v237
	v_add_f32_e32 v240, v240, v241
	v_add_f32_e32 v216, v216, v217
	v_add_f32_e32 v220, v220, v221
	v_add_f32_e32 v142, v142, v143
	v_add_f32_e32 v146, v146, v147
	v_fmaak_f32 v228, v245, v228, 0x358637bd
	v_fmaak_f32 v232, v245, v232, 0x358637bd
	v_fmaak_f32 v236, v245, v236, 0x358637bd
	v_fmaak_f32 v240, v245, v240, 0x358637bd
	v_fmaak_f32 v216, v245, v216, 0x358637bd
	v_fmaak_f32 v220, v245, v220, 0x358637bd
	v_fmaak_f32 v142, v245, v142, 0x358637bd
	v_fmaak_f32 v146, v245, v146, 0x358637bd
	v_rsq_f32_e32 v244, v228
	v_rsq_f32_e32 v245, v232
	v_rsq_f32_e32 v246, v236
	v_rsq_f32_e32 v247, v240
	v_rsq_f32_e32 v248, v216
	v_rsq_f32_e32 v249, v220
	v_rsq_f32_e32 v250, v142
	v_rsq_f32_e32 v251, v146
	s_mov_b64 s[4:5], -1
	s_mov_b64 s[10:11], 0
	s_cmp_lt_i32 s66, 4
	s_mov_b64 s[80:81], 0
	s_cbranch_scc1 .LBB0_1744
	s_cmp_gt_i32 s66, 5
	s_cbranch_scc0 .LBB0_1738
	s_cmp_gt_i32 s66, 6
	s_cbranch_scc0 .LBB0_1735
	s_cmp_gt_i32 s66, 7
	s_cbranch_scc0 .LBB0_1732
	s_cmp_eq_u32 s66, 8
	s_mov_b64 s[80:81], -1
	s_cbranch_scc0 .LBB0_1731
	s_lshl_b32 s4, s43, 6
	s_lshl_b32 s5, s34, 8
	s_add_i32 s4, s4, s5
	v_add_u32_e32 v160, s4, v214
	v_ashrrev_i32_e32 v161, 31, v160
	v_lshlrev_b64 v[128:129], 6, v[160:161]
	v_lshl_add_u64 v[140:141], s[70:71], 0, v[128:129]
	s_nop 0
	v_add_u32_e32 v190, 16, v160
	v_ashrrev_i32_e32 v191, 31, v190
	s_mov_b32 s4, 0x358637bd
	s_mov_b32 s6, 0x3a800000
	v_add_u32_e32 v166, 32, v160
	v_ashrrev_i32_e32 v167, 31, v166
	v_add_u32_e32 v168, 48, v160
	v_ashrrev_i32_e32 v169, 31, v168
	v_add_u32_e32 v164, 0x80, v160
	s_movk_i32 s8, 0x2800
	s_mov_b64 s[12:13], 0x126000
	s_mov_b32 s9, 0x126000
	v_add_u32_e32 v163, 0xffffc080, v160
	v_mov_b32_e32 v165, 0xffffc400
	v_mov_b32_e32 v171, 0x4000
	s_nop 0
	v_lshlrev_b64 v[128:129], 6, v[190:191]
	v_lshl_add_u64 v[140:141], s[70:71], 0, v[128:129]
	s_nop 0
	s_nop 0
	v_mov_b64_e32 v[128:129], s[4:5]
	s_nop 0
	s_nop 0
	s_nop 0
	v_mov_b32_e32 v192, v244
	s_nop 0
	v_mov_b32_e32 v162, v245
	v_lshlrev_b64 v[130:131], 6, v[166:167]
	v_lshl_add_u64 v[142:143], s[70:71], 0, v[130:131]
	s_nop 0
	s_nop 0
	v_lshlrev_b64 v[130:131], 6, v[168:169]
	v_lshl_add_u64 v[142:143], s[70:71], 0, v[130:131]
	s_nop 0
	s_nop 0
	s_nop 0
	s_nop 0
	s_nop 0
	s_nop 0
	v_mov_b32_e32 v172, v246
	s_nop 0
	v_mov_b32_e32 v188, v247
	v_mov_b32 v130, 0
	s_nop 0
	v_add_u32_e32 v130, v130, v164
	v_ashrrev_i32_e32 v131, 31, v130
	v_lshlrev_b64 v[132:133], 6, v[130:131]
	v_lshl_add_u64 v[144:145], s[70:71], 0, v[132:133]
	s_nop 0
	s_nop 0
	v_add_u32_e32 v132, 16, v130
	v_ashrrev_i32_e32 v133, 31, v132
	v_lshlrev_b64 v[132:133], 6, v[132:133]
	v_lshl_add_u64 v[144:145], s[70:71], 0, v[132:133]
	s_nop 0
;     template <int PN> DI void body(AccRef acc, const Unit& u, int wr, int wc, int fr, int fq) const {
;     ...
;                     float* lo = orow(out, l, row, PN == 8 ? O_PSK : O_PSV, PN == 8 ? O_SSK : O_SSV, 256);
; #pragma unroll
;                     for (int bj = 0; bj < 2; ++bj) {
;                         *(f32x4*)(lo + bj * 128 + cl) = (f32x4){v[bj][0], v[bj][1], v[bj][2], v[bj][3]};
;                         *(f32x4*)(lo + bj * 128 + cl + 4) = (f32x4){v[bj][4], v[bj][5], v[bj][6], v[bj][7]};
;                     }
	s_nop 0
	s_nop 0
	s_nop 0
	s_nop 0
	s_nop 0
	v_mov_b32_e32 v174, v248
	s_nop 0
	v_mov_b32_e32 v170, v249
	v_add_u32_e32 v132, 32, v130
	v_ashrrev_i32_e32 v133, 31, v132
	v_lshlrev_b64 v[132:133], 6, v[132:133]
	v_lshl_add_u64 v[144:145], s[70:71], 0, v[132:133]
	s_nop 0
	v_add_u32_e32 v130, 48, v130
	v_ashrrev_i32_e32 v131, 31, v130
	v_lshlrev_b64 v[130:131], 6, v[130:131]
	v_lshl_add_u64 v[142:143], s[70:71], 0, v[130:131]
	s_nop 0
	s_nop 0
	s_nop 0
	s_nop 0
	s_nop 0
	s_nop 0
	v_mov_b32_e32 v196, v250
	s_lshl_b32 s4, s54, 5
	v_lshl_add_u32 v198, v213, 3, s4
	v_cmp_gt_i32_e64 s[4:5], s94, v160
	v_mov_b32_e32 v194, v251
	v_add_u32_e32 v129, 0xffffc000, v160
	v_lshrrev_b32_e32 v129, 6, v129
	v_ashrrev_i32_e32 v128, 11, v160
	v_add_u32_e32 v129, 8, v129
	v_cndmask_b32_e64 v128, v129, v128, s[4:5]
	v_mov_b32 v134, 0
	v_ashrrev_i32_e32 v199, 31, v198
	v_add_u32_e32 v130, v134, v128
	v_mov_b64_e32 v[128:129], s[60:61]
	v_mad_i64_i32 v[130:131], s[6:7], v130, s8, v[128:129]
	v_lshlrev_b64 v[200:201], 2, v[198:199]
	v_lshl_add_u64 v[130:131], v[130:131], 0, v[200:201]
	v_lshl_add_u64 v[132:133], v[130:131], 0, s[12:13]
	v_add_co_u32_e32 v130, vcc, s9, v130
	s_movk_i32 s6, 0x3fff
	s_nop 0
	v_addc_co_u32_e32 v131, vcc, 0, v131, vcc
	global_load_dwordx4 v[152:155], v[130:131], off
	global_load_dwordx4 v[156:159], v[132:133], off offset:16
	global_load_dwordx4 v[144:147], v[132:133], off offset:528
	global_load_dwordx4 v[148:151], v[132:133], off offset:512
	v_lshrrev_b32_e32 v131, 6, v163
	v_cmp_lt_i32_e32 vcc, s6, v164
	v_cmp_gt_i32_e64 s[6:7], s94, v164
	v_ashrrev_i32_e32 v130, 11, v164
	v_add_u32_e32 v131, 8, v131
	v_cndmask_b32_e64 v130, v131, v130, s[6:7]
	v_add_u32_e32 v130, v134, v130
	v_mad_i64_i32 v[128:129], s[6:7], v130, s8, v[128:129]
	v_lshl_add_u64 v[128:129], v[128:129], 0, v[200:201]
	v_lshl_add_u64 v[132:133], v[128:129], 0, s[12:13]
	v_add_co_u32_e64 v128, s[6:7], s9, v128
	v_cndmask_b32_e64 v203, -1, 0, s[4:5]
	s_nop 0
	v_addc_co_u32_e64 v129, s[6:7], 0, v129, s[6:7]
	global_load_dwordx4 v[140:143], v[128:129], off
	global_load_dwordx4 v[136:139], v[132:133], off offset:16
	s_nop 0
	global_load_dwordx4 v[128:131], v[132:133], off offset:528
	s_nop 0
	global_load_dwordx4 v[132:135], v[132:133], off offset:512
	v_cndmask_b32_e64 v202, v165, v171, s[4:5]
	v_mov_b32_e32 v165, 0xab98000
	v_mov_b32_e32 v171, 0x6800000
	v_lshl_add_u64 v[202:203], v[202:203], 0, v[160:161]
	v_cndmask_b32_e64 v224, v165, v171, s[4:5]
	v_lshl_add_u64 v[204:205], s[84:85], 0, v[224:225]
	v_lshlrev_b64 v[202:203], 10, v[202:203]
	v_lshl_add_u64 v[202:203], v[204:205], 0, v[202:203]
	v_lshl_add_u64 v[206:207], v[202:203], 0, v[200:201]
	s_movk_i32 s6, 0xc410
	v_mov_b32_e32 v224, v160
	s_mov_b32 s7, -1
	v_cmp_gt_i32_e64 s[4:5], s82, v160
	s_movk_i32 s8, 0xc420
	s_mov_b32 s9, -1
	s_waitcnt vmcnt(7)
	v_pk_fma_f32 v[204:205], v[126:127], v[192:193], v[154:155] op_sel_hi:[1,0,1]
	v_pk_fma_f32 v[202:203], v[124:125], v[192:193], v[152:153] op_sel_hi:[1,0,1]
	s_mov_b32 s98, 0xff00ff
	s_mov_b32 s99, 0xff00ff
	s_mov_b32 s32, 0xffffe010
	s_mov_b32 s100, 0xffffdff0
	s_movk_i32 s101, 0x1ff0
	v_mov_b32_e32 v244, v202
	v_mov_b32_e32 v245, v203
	v_mov_b32_e32 v246, v204
	v_mov_b32_e32 v247, v205
	s_waitcnt vmcnt(6)
	s_nop 0
	v_pk_fma_f32 v[204:205], v[122:123], v[192:193], v[158:159] op_sel_hi:[1,0,1]
	v_pk_fma_f32 v[202:203], v[120:121], v[192:193], v[156:157] op_sel_hi:[1,0,1]
	s_nop 1
	v_mov_b32_dpp v248, v202 row_ror:8 row_mask:0xf bank_mask:0xf
	v_mov_b32_dpp v249, v203 row_ror:8 row_mask:0xf bank_mask:0xf
	v_mov_b32_dpp v250, v204 row_ror:8 row_mask:0xf bank_mask:0xf
	v_mov_b32_dpp v251, v205 row_ror:8 row_mask:0xf bank_mask:0xf
	v_cndmask_b32_e64 v202, v248, v244, s[98:99]
	v_cndmask_b32_e64 v203, v249, v245, s[98:99]
	v_cndmask_b32_e64 v204, v250, v246, s[98:99]
	v_cndmask_b32_e64 v205, v251, v247, s[98:99]
	v_cndmask_b32_e64 v244, v244, v248, s[98:99]
	v_cndmask_b32_e64 v245, v245, v249, s[98:99]
	v_cndmask_b32_e64 v246, v246, v250, s[98:99]
	v_cndmask_b32_e64 v247, v247, v251, s[98:99]
	v_cndmask_b32_e64 v250, 1, 0, s[98:99]
	v_cndmask_b32_e64 v251, 0, 1, s[98:99]
	v_mul_i32_i24_e32 v248, s32, v250
	v_sub_u32_e32 v249, 0, v250
	v_lshl_add_u64 v[206:207], v[206:207], 0, v[248:249]
	global_store_dwordx4 v[206:207], v[202:205], off
	v_lshl_add_u32 v248, v251, 5, s101
	v_mov_b32_e32 v249, 0
	v_lshl_add_u64 v[206:207], v[206:207], 0, v[248:249]
	global_store_dwordx4 v[206:207], v[244:247], off
	v_mul_i32_i24_e32 v248, s100, v251
	v_sub_u32_e32 v249, 0, v251
	v_lshl_add_u64 v[206:207], v[206:207], 0, v[248:249]
	s_waitcnt vmcnt(5)
;     template <int PN> DI void body(AccRef acc, const Unit& u, int wr, int wc, int fr, int fq) const {
;     ...
;                     float* lo = orow(out, l, row, PN == 8 ? O_PSK : O_PSV, PN == 8 ? O_SSK : O_SSV, 256);
; #pragma unroll
;                     for (int bj = 0; bj < 2; ++bj) {
;                         *(f32x4*)(lo + bj * 128 + cl) = (f32x4){v[bj][0], v[bj][1], v[bj][2], v[bj][3]};
;                         *(f32x4*)(lo + bj * 128 + cl + 4) = (f32x4){v[bj][4], v[bj][5], v[bj][6], v[bj][7]};
;                     }
	s_nop 0
	v_pk_fma_f32 v[204:205], v[118:119], v[192:193], v[150:151] op_sel_hi:[1,0,1]
	v_pk_fma_f32 v[202:203], v[116:117], v[192:193], v[148:149] op_sel_hi:[1,0,1]
	v_mov_b32_e32 v244, v202
	v_mov_b32_e32 v245, v203
	v_mov_b32_e32 v246, v204
	v_mov_b32_e32 v247, v205
	s_nop 1
	v_pk_fma_f32 v[204:205], v[114:115], v[192:193], v[146:147] op_sel_hi:[1,0,1]
	v_pk_fma_f32 v[202:203], v[112:113], v[192:193], v[144:145] op_sel_hi:[1,0,1]
	v_lshl_add_u64 v[192:193], v[224:225], 0, s[6:7]
	s_mov_b64 s[6:7], 0x4000
	v_lshl_add_u64 v[190:191], v[190:191], 0, s[6:7]
	v_cndmask_b32_e64 v191, v193, v191, s[4:5]
	v_cndmask_b32_e64 v190, v192, v190, s[4:5]
	v_cndmask_b32_e64 v192, v165, v171, s[4:5]
	v_mov_b32_e32 v193, v225
	v_lshl_add_u64 v[192:193], s[84:85], 0, v[192:193]
	v_lshlrev_b64 v[190:191], 10, v[190:191]
	v_lshl_add_u64 v[190:191], v[192:193], 0, v[190:191]
	s_nop 1
	v_mov_b32_dpp v248, v202 row_ror:8 row_mask:0xf bank_mask:0xf
	v_mov_b32_dpp v249, v203 row_ror:8 row_mask:0xf bank_mask:0xf
	v_mov_b32_dpp v250, v204 row_ror:8 row_mask:0xf bank_mask:0xf
	v_mov_b32_dpp v251, v205 row_ror:8 row_mask:0xf bank_mask:0xf
	v_cndmask_b32_e64 v202, v248, v244, s[98:99]
	v_cndmask_b32_e64 v203, v249, v245, s[98:99]
	v_cndmask_b32_e64 v204, v250, v246, s[98:99]
	v_cndmask_b32_e64 v205, v251, v247, s[98:99]
	v_cndmask_b32_e64 v244, v244, v248, s[98:99]
	v_cndmask_b32_e64 v245, v245, v249, s[98:99]
	v_cndmask_b32_e64 v246, v246, v250, s[98:99]
	v_cndmask_b32_e64 v247, v247, v251, s[98:99]
	v_cndmask_b32_e64 v250, 1, 0, s[98:99]
	v_cndmask_b32_e64 v251, 0, 1, s[98:99]
	v_mul_i32_i24_e32 v248, s32, v250
	v_sub_u32_e32 v249, 0, v250
	v_lshl_add_u64 v[206:207], v[206:207], 0, v[248:249]
	global_store_dwordx4 v[206:207], v[202:205], off offset:512
	v_lshl_add_u32 v248, v251, 5, s101
	v_mov_b32_e32 v249, 0
	v_lshl_add_u64 v[206:207], v[206:207], 0, v[248:249]
	global_store_dwordx4 v[206:207], v[244:247], off offset:512
	v_mul_i32_i24_e32 v248, s100, v251
	v_sub_u32_e32 v249, 0, v251
	v_lshl_add_u64 v[206:207], v[206:207], 0, v[248:249]
	v_pk_fma_f32 v[192:193], v[110:111], v[162:163], v[154:155] op_sel_hi:[1,0,1]
	v_cmp_gt_i32_e64 s[4:5], s83, v160
	v_lshl_add_u64 v[202:203], v[190:191], 0, v[200:201]
	v_pk_fma_f32 v[190:191], v[108:109], v[162:163], v[152:153] op_sel_hi:[1,0,1]
	v_mov_b32_e32 v244, v190
	v_mov_b32_e32 v245, v191
	v_mov_b32_e32 v246, v192
	v_mov_b32_e32 v247, v193
	v_lshl_add_u64 v[166:167], v[166:167], 0, s[6:7]
	s_nop 0
	v_pk_fma_f32 v[192:193], v[106:107], v[162:163], v[158:159] op_sel_hi:[1,0,1]
	v_pk_fma_f32 v[190:191], v[104:105], v[162:163], v[156:157] op_sel_hi:[1,0,1]
	s_nop 1
	v_mov_b32_dpp v248, v190 row_ror:8 row_mask:0xf bank_mask:0xf
	v_mov_b32_dpp v249, v191 row_ror:8 row_mask:0xf bank_mask:0xf
	v_mov_b32_dpp v250, v192 row_ror:8 row_mask:0xf bank_mask:0xf
	v_mov_b32_dpp v251, v193 row_ror:8 row_mask:0xf bank_mask:0xf
	v_cndmask_b32_e64 v190, v248, v244, s[98:99]
	v_cndmask_b32_e64 v191, v249, v245, s[98:99]
	v_cndmask_b32_e64 v192, v250, v246, s[98:99]
	v_cndmask_b32_e64 v193, v251, v247, s[98:99]
	v_cndmask_b32_e64 v244, v244, v248, s[98:99]
	v_cndmask_b32_e64 v245, v245, v249, s[98:99]
	v_cndmask_b32_e64 v246, v246, v250, s[98:99]
	v_cndmask_b32_e64 v247, v247, v251, s[98:99]
	v_cndmask_b32_e64 v250, 1, 0, s[98:99]
	v_cndmask_b32_e64 v251, 0, 1, s[98:99]
	v_mul_i32_i24_e32 v248, s32, v250
	v_sub_u32_e32 v249, 0, v250
	v_lshl_add_u64 v[202:203], v[202:203], 0, v[248:249]
	global_store_dwordx4 v[202:203], v[190:193], off
	v_lshl_add_u32 v248, v251, 5, s101
	v_mov_b32_e32 v249, 0
	v_lshl_add_u64 v[202:203], v[202:203], 0, v[248:249]
	global_store_dwordx4 v[202:203], v[244:247], off
	v_mul_i32_i24_e32 v248, s100, v251
	v_sub_u32_e32 v249, 0, v251
	v_lshl_add_u64 v[202:203], v[202:203], 0, v[248:249]
	s_nop 1
	v_pk_fma_f32 v[192:193], v[102:103], v[162:163], v[150:151] op_sel_hi:[1,0,1]
	v_pk_fma_f32 v[190:191], v[100:101], v[162:163], v[148:149] op_sel_hi:[1,0,1]
	v_mov_b32_e32 v244, v190
	v_mov_b32_e32 v245, v191
	v_mov_b32_e32 v246, v192
	v_mov_b32_e32 v247, v193
	s_nop 1
	v_pk_fma_f32 v[192:193], v[98:99], v[162:163], v[146:147] op_sel_hi:[1,0,1]
	v_pk_fma_f32 v[190:191], v[96:97], v[162:163], v[144:145] op_sel_hi:[1,0,1]
	s_nop 1
	v_mov_b32_dpp v248, v190 row_ror:8 row_mask:0xf bank_mask:0xf
	v_mov_b32_dpp v249, v191 row_ror:8 row_mask:0xf bank_mask:0xf
	v_mov_b32_dpp v250, v192 row_ror:8 row_mask:0xf bank_mask:0xf
	v_mov_b32_dpp v251, v193 row_ror:8 row_mask:0xf bank_mask:0xf
	v_cndmask_b32_e64 v190, v248, v244, s[98:99]
	v_cndmask_b32_e64 v191, v249, v245, s[98:99]
	v_cndmask_b32_e64 v192, v250, v246, s[98:99]
	v_cndmask_b32_e64 v193, v251, v247, s[98:99]
	v_cndmask_b32_e64 v244, v244, v248, s[98:99]
	v_cndmask_b32_e64 v245, v245, v249, s[98:99]
	v_cndmask_b32_e64 v246, v246, v250, s[98:99]
	v_cndmask_b32_e64 v247, v247, v251, s[98:99]
	v_cndmask_b32_e64 v250, 1, 0, s[98:99]
	v_cndmask_b32_e64 v251, 0, 1, s[98:99]
	v_mul_i32_i24_e32 v248, s32, v250
	v_sub_u32_e32 v249, 0, v250
	v_lshl_add_u64 v[202:203], v[202:203], 0, v[248:249]
	global_store_dwordx4 v[202:203], v[190:193], off offset:512
	v_lshl_add_u32 v248, v251, 5, s101
	v_mov_b32_e32 v249, 0
	v_lshl_add_u64 v[202:203], v[202:203], 0, v[248:249]
	global_store_dwordx4 v[202:203], v[244:247], off offset:512
	v_mul_i32_i24_e32 v248, s100, v251
	v_sub_u32_e32 v249, 0, v251
	v_lshl_add_u64 v[202:203], v[202:203], 0, v[248:249]
	s_nop 1
	v_lshl_add_u64 v[190:191], v[224:225], 0, s[8:9]
	v_cndmask_b32_e64 v167, v191, v167, s[4:5]
	v_cndmask_b32_e64 v166, v190, v166, s[4:5]
	v_cndmask_b32_e64 v190, v165, v171, s[4:5]
	v_mov_b32_e32 v191, v225
	v_lshl_add_u64 v[190:191], s[84:85], 0, v[190:191]
;     template <int PN> DI void body(AccRef acc, const Unit& u, int wr, int wc, int fr, int fq) const {
;     ...
;                     float* lo = orow(out, l, row, PN == 8 ? O_PSK : O_PSV, PN == 8 ? O_SSK : O_SSV, 256);
; #pragma unroll
;                     for (int bj = 0; bj < 2; ++bj) {
;                         *(f32x4*)(lo + bj * 128 + cl) = (f32x4){v[bj][0], v[bj][1], v[bj][2], v[bj][3]};
;                         *(f32x4*)(lo + bj * 128 + cl + 4) = (f32x4){v[bj][4], v[bj][5], v[bj][6], v[bj][7]};
;                     }
	v_lshlrev_b64 v[166:167], 10, v[166:167]
	v_lshl_add_u64 v[166:167], v[190:191], 0, v[166:167]
	v_lshl_add_u64 v[166:167], v[166:167], 0, v[200:201]
	v_pk_fma_f32 v[192:193], v[94:95], v[172:173], v[154:155] op_sel_hi:[1,0,1]
	v_pk_fma_f32 v[190:191], v[92:93], v[172:173], v[152:153] op_sel_hi:[1,0,1]
	v_mov_b32_e32 v244, v190
	v_mov_b32_e32 v245, v191
	v_mov_b32_e32 v246, v192
	v_mov_b32_e32 v247, v193
	s_movk_i32 s8, 0xc430
	s_mov_b32 s9, -1
	v_pk_fma_f32 v[192:193], v[90:91], v[172:173], v[158:159] op_sel_hi:[1,0,1]
	v_pk_fma_f32 v[190:191], v[88:89], v[172:173], v[156:157] op_sel_hi:[1,0,1]
	s_nop 1
	v_mov_b32_dpp v248, v190 row_ror:8 row_mask:0xf bank_mask:0xf
	v_mov_b32_dpp v249, v191 row_ror:8 row_mask:0xf bank_mask:0xf
	v_mov_b32_dpp v250, v192 row_ror:8 row_mask:0xf bank_mask:0xf
	v_mov_b32_dpp v251, v193 row_ror:8 row_mask:0xf bank_mask:0xf
	v_cndmask_b32_e64 v190, v248, v244, s[98:99]
	v_cndmask_b32_e64 v191, v249, v245, s[98:99]
	v_cndmask_b32_e64 v192, v250, v246, s[98:99]
	v_cndmask_b32_e64 v193, v251, v247, s[98:99]
	v_cndmask_b32_e64 v244, v244, v248, s[98:99]
	v_cndmask_b32_e64 v245, v245, v249, s[98:99]
	v_cndmask_b32_e64 v246, v246, v250, s[98:99]
	v_cndmask_b32_e64 v247, v247, v251, s[98:99]
	v_cndmask_b32_e64 v250, 1, 0, s[98:99]
	v_cndmask_b32_e64 v251, 0, 1, s[98:99]
	v_mul_i32_i24_e32 v248, s32, v250
	v_sub_u32_e32 v249, 0, v250
	v_lshl_add_u64 v[166:167], v[166:167], 0, v[248:249]
	global_store_dwordx4 v[166:167], v[190:193], off
	v_lshl_add_u32 v248, v251, 5, s101
	v_mov_b32_e32 v249, 0
	v_lshl_add_u64 v[166:167], v[166:167], 0, v[248:249]
	global_store_dwordx4 v[166:167], v[244:247], off
	v_mul_i32_i24_e32 v248, s100, v251
	v_sub_u32_e32 v249, 0, v251
	v_lshl_add_u64 v[166:167], v[166:167], 0, v[248:249]
	v_cmp_gt_i32_e64 s[4:5], s92, v160
	v_lshl_add_u64 v[160:161], v[224:225], 0, s[8:9]
	v_pk_fma_f32 v[192:193], v[86:87], v[172:173], v[150:151] op_sel_hi:[1,0,1]
	v_pk_fma_f32 v[190:191], v[84:85], v[172:173], v[148:149] op_sel_hi:[1,0,1]
	v_mov_b32_e32 v244, v190
	v_mov_b32_e32 v245, v191
	v_mov_b32_e32 v246, v192
	v_mov_b32_e32 v247, v193
	v_pk_fma_f32 v[154:155], v[78:79], v[188:189], v[154:155] op_sel_hi:[1,0,1]
	v_pk_fma_f32 v[152:153], v[76:77], v[188:189], v[152:153] op_sel_hi:[1,0,1]
	v_pk_fma_f32 v[192:193], v[82:83], v[172:173], v[146:147] op_sel_hi:[1,0,1]
	v_pk_fma_f32 v[190:191], v[80:81], v[172:173], v[144:145] op_sel_hi:[1,0,1]
	s_nop 1
	v_mov_b32_dpp v248, v190 row_ror:8 row_mask:0xf bank_mask:0xf
	v_mov_b32_dpp v249, v191 row_ror:8 row_mask:0xf bank_mask:0xf
	v_mov_b32_dpp v250, v192 row_ror:8 row_mask:0xf bank_mask:0xf
	v_mov_b32_dpp v251, v193 row_ror:8 row_mask:0xf bank_mask:0xf
	v_cndmask_b32_e64 v190, v248, v244, s[98:99]
	v_cndmask_b32_e64 v191, v249, v245, s[98:99]
	v_cndmask_b32_e64 v192, v250, v246, s[98:99]
	v_cndmask_b32_e64 v193, v251, v247, s[98:99]
	v_cndmask_b32_e64 v244, v244, v248, s[98:99]
	v_cndmask_b32_e64 v245, v245, v249, s[98:99]
	v_cndmask_b32_e64 v246, v246, v250, s[98:99]
	v_cndmask_b32_e64 v247, v247, v251, s[98:99]
	v_cndmask_b32_e64 v250, 1, 0, s[98:99]
	v_cndmask_b32_e64 v251, 0, 1, s[98:99]
	v_mul_i32_i24_e32 v248, s32, v250
	v_sub_u32_e32 v249, 0, v250
	v_lshl_add_u64 v[166:167], v[166:167], 0, v[248:249]
	global_store_dwordx4 v[166:167], v[190:193], off offset:512
	v_lshl_add_u32 v248, v251, 5, s101
	v_mov_b32_e32 v249, 0
	v_lshl_add_u64 v[166:167], v[166:167], 0, v[248:249]
	global_store_dwordx4 v[166:167], v[244:247], off offset:512
	v_mul_i32_i24_e32 v248, s100, v251
	v_sub_u32_e32 v249, 0, v251
	v_lshl_add_u64 v[166:167], v[166:167], 0, v[248:249]
	v_lshl_add_u64 v[166:167], v[168:169], 0, s[6:7]
	v_cndmask_b32_e64 v161, v161, v167, s[4:5]
	v_cndmask_b32_e64 v160, v160, v166, s[4:5]
	v_cndmask_b32_e64 v166, v165, v171, s[4:5]
	v_mov_b32_e32 v167, v225
	v_lshl_add_u64 v[166:167], s[84:85], 0, v[166:167]
	v_lshlrev_b64 v[160:161], 10, v[160:161]
	v_lshl_add_u64 v[160:161], v[166:167], 0, v[160:161]
	v_lshl_add_u64 v[160:161], v[160:161], 0, v[200:201]
	v_mov_b32_e32 v244, v152
	v_mov_b32_e32 v245, v153
	v_mov_b32_e32 v246, v154
	v_mov_b32_e32 v247, v155
	v_pk_fma_f32 v[150:151], v[70:71], v[188:189], v[150:151] op_sel_hi:[1,0,1]
	v_pk_fma_f32 v[148:149], v[68:69], v[188:189], v[148:149] op_sel_hi:[1,0,1]
	v_pk_fma_f32 v[154:155], v[74:75], v[188:189], v[158:159] op_sel_hi:[1,0,1]
	v_pk_fma_f32 v[152:153], v[72:73], v[188:189], v[156:157] op_sel_hi:[1,0,1]
	v_pk_fma_f32 v[146:147], v[66:67], v[188:189], v[146:147] op_sel_hi:[1,0,1]
	v_pk_fma_f32 v[144:145], v[64:65], v[188:189], v[144:145] op_sel_hi:[1,0,1]
	s_nop 1
	v_mov_b32_dpp v248, v152 row_ror:8 row_mask:0xf bank_mask:0xf
	v_mov_b32_dpp v249, v153 row_ror:8 row_mask:0xf bank_mask:0xf
	v_mov_b32_dpp v250, v154 row_ror:8 row_mask:0xf bank_mask:0xf
	v_mov_b32_dpp v251, v155 row_ror:8 row_mask:0xf bank_mask:0xf
	v_cndmask_b32_e64 v152, v248, v244, s[98:99]
	v_cndmask_b32_e64 v153, v249, v245, s[98:99]
	v_cndmask_b32_e64 v154, v250, v246, s[98:99]
	v_cndmask_b32_e64 v155, v251, v247, s[98:99]
	v_cndmask_b32_e64 v244, v244, v248, s[98:99]
	v_cndmask_b32_e64 v245, v245, v249, s[98:99]
	v_cndmask_b32_e64 v246, v246, v250, s[98:99]
	v_cndmask_b32_e64 v247, v247, v251, s[98:99]
	v_cndmask_b32_e64 v250, 1, 0, s[98:99]
	v_cndmask_b32_e64 v251, 0, 1, s[98:99]
	v_mul_i32_i24_e32 v248, s32, v250
	v_sub_u32_e32 v249, 0, v250
	v_lshl_add_u64 v[160:161], v[160:161], 0, v[248:249]
	global_store_dwordx4 v[160:161], v[152:155], off
	v_lshl_add_u32 v248, v251, 5, s101
	v_mov_b32_e32 v249, 0
	v_lshl_add_u64 v[160:161], v[160:161], 0, v[248:249]
	global_store_dwordx4 v[160:161], v[244:247], off
	v_mul_i32_i24_e32 v248, s100, v251
;     template <int PN> DI void body(AccRef acc, const Unit& u, int wr, int wc, int fr, int fq) const {
;     ...
;                     float* lo = orow(out, l, row, PN == 8 ? O_PSK : O_PSV, PN == 8 ? O_SSK : O_SSV, 256);
; #pragma unroll
;                     for (int bj = 0; bj < 2; ++bj) {
;                         *(f32x4*)(lo + bj * 128 + cl) = (f32x4){v[bj][0], v[bj][1], v[bj][2], v[bj][3]};
;                         *(f32x4*)(lo + bj * 128 + cl + 4) = (f32x4){v[bj][4], v[bj][5], v[bj][6], v[bj][7]};
;                     }
	v_sub_u32_e32 v249, 0, v251
	v_lshl_add_u64 v[160:161], v[160:161], 0, v[248:249]
	v_mov_b32_e32 v244, v148
	v_mov_b32_e32 v245, v149
	v_mov_b32_e32 v246, v150
	v_mov_b32_e32 v247, v151
	s_nop 1
	v_mov_b32_dpp v248, v144 row_ror:8 row_mask:0xf bank_mask:0xf
	v_mov_b32_dpp v249, v145 row_ror:8 row_mask:0xf bank_mask:0xf
	v_mov_b32_dpp v250, v146 row_ror:8 row_mask:0xf bank_mask:0xf
	v_mov_b32_dpp v251, v147 row_ror:8 row_mask:0xf bank_mask:0xf
	v_cndmask_b32_e64 v144, v248, v244, s[98:99]
	v_cndmask_b32_e64 v145, v249, v245, s[98:99]
	v_cndmask_b32_e64 v146, v250, v246, s[98:99]
	v_cndmask_b32_e64 v147, v251, v247, s[98:99]
	v_cndmask_b32_e64 v244, v244, v248, s[98:99]
	v_cndmask_b32_e64 v245, v245, v249, s[98:99]
	v_cndmask_b32_e64 v246, v246, v250, s[98:99]
	v_cndmask_b32_e64 v247, v247, v251, s[98:99]
	v_cndmask_b32_e64 v250, 1, 0, s[98:99]
	v_cndmask_b32_e64 v251, 0, 1, s[98:99]
	v_mul_i32_i24_e32 v248, s32, v250
	v_sub_u32_e32 v249, 0, v250
	v_lshl_add_u64 v[160:161], v[160:161], 0, v[248:249]
	global_store_dwordx4 v[160:161], v[144:147], off offset:512
	v_lshl_add_u32 v248, v251, 5, s101
	v_mov_b32_e32 v249, 0
	v_lshl_add_u64 v[160:161], v[160:161], 0, v[248:249]
	global_store_dwordx4 v[160:161], v[244:247], off offset:512
	v_mul_i32_i24_e32 v248, s100, v251
	v_sub_u32_e32 v249, 0, v251
	v_lshl_add_u64 v[160:161], v[160:161], 0, v[248:249]
	s_and_saveexec_b64 s[4:5], vcc
	s_xor_b64 s[4:5], exec, s[4:5]
	v_add_u32_e32 v144, 0x400, v163
	v_mov_b32_e32 v145, v225
	s_or_saveexec_b64 s[4:5], s[4:5]
	v_mov_b64_e32 v[146:147], 0x2ae6000
	s_xor_b64 exec, exec, s[4:5]
	v_ashrrev_i32_e32 v165, 31, v164
	v_lshl_add_u64 v[144:145], v[164:165], 0, s[6:7]
	v_mov_b64_e32 v[146:147], 0x1a00000
	s_or_b64 exec, exec, s[4:5]
	v_lshlrev_b32_e32 v146, 2, v146
	v_mov_b32_e32 v147, v225
	v_lshl_add_u64 v[146:147], s[84:85], 0, v[146:147]
	v_lshlrev_b64 v[144:145], 10, v[144:145]
	v_lshl_add_u64 v[144:145], v[146:147], 0, v[144:145]
	v_lshl_add_u64 v[148:149], v[198:199], 2, v[144:145]
	s_waitcnt vmcnt(18)
	v_pk_fma_f32 v[146:147], v[62:63], v[174:175], v[142:143] op_sel_hi:[1,0,1]
	v_pk_fma_f32 v[144:145], v[60:61], v[174:175], v[140:141] op_sel_hi:[1,0,1]
	v_mov_b32_e32 v244, v144
	v_mov_b32_e32 v245, v145
	v_mov_b32_e32 v246, v146
	v_mov_b32_e32 v247, v147
	s_movk_i32 s4, 0x3fef
	v_cmp_lt_i32_e32 vcc, s4, v164
	s_waitcnt vmcnt(18)
	v_pk_fma_f32 v[146:147], v[58:59], v[174:175], v[138:139] op_sel_hi:[1,0,1]
	v_pk_fma_f32 v[144:145], v[56:57], v[174:175], v[136:137] op_sel_hi:[1,0,1]
	s_nop 1
	v_mov_b32_dpp v248, v144 row_ror:8 row_mask:0xf bank_mask:0xf
	v_mov_b32_dpp v249, v145 row_ror:8 row_mask:0xf bank_mask:0xf
	v_mov_b32_dpp v250, v146 row_ror:8 row_mask:0xf bank_mask:0xf
	v_mov_b32_dpp v251, v147 row_ror:8 row_mask:0xf bank_mask:0xf
	v_cndmask_b32_e64 v144, v248, v244, s[98:99]
	v_cndmask_b32_e64 v145, v249, v245, s[98:99]
	v_cndmask_b32_e64 v146, v250, v246, s[98:99]
	v_cndmask_b32_e64 v147, v251, v247, s[98:99]
	v_cndmask_b32_e64 v244, v244, v248, s[98:99]
	v_cndmask_b32_e64 v245, v245, v249, s[98:99]
	v_cndmask_b32_e64 v246, v246, v250, s[98:99]
	v_cndmask_b32_e64 v247, v247, v251, s[98:99]
	v_cndmask_b32_e64 v250, 1, 0, s[98:99]
	v_cndmask_b32_e64 v251, 0, 1, s[98:99]
	v_mul_i32_i24_e32 v248, s32, v250
	v_sub_u32_e32 v249, 0, v250
	v_lshl_add_u64 v[148:149], v[148:149], 0, v[248:249]
	global_store_dwordx4 v[148:149], v[144:147], off
	v_lshl_add_u32 v248, v251, 5, s101
	v_mov_b32_e32 v249, 0
	v_lshl_add_u64 v[148:149], v[148:149], 0, v[248:249]
	global_store_dwordx4 v[148:149], v[244:247], off
	v_mul_i32_i24_e32 v248, s100, v251
	v_sub_u32_e32 v249, 0, v251
	v_lshl_add_u64 v[148:149], v[148:149], 0, v[248:249]
	s_waitcnt vmcnt(17)
	s_nop 0
	v_pk_fma_f32 v[146:147], v[54:55], v[174:175], v[134:135] op_sel_hi:[1,0,1]
	v_pk_fma_f32 v[144:145], v[52:53], v[174:175], v[132:133] op_sel_hi:[1,0,1]
	v_mov_b32_e32 v244, v144
	v_mov_b32_e32 v245, v145
	v_mov_b32_e32 v246, v146
	v_mov_b32_e32 v247, v147
	s_nop 1
	v_pk_fma_f32 v[146:147], v[50:51], v[174:175], v[130:131] op_sel_hi:[1,0,1]
	v_pk_fma_f32 v[144:145], v[48:49], v[174:175], v[128:129] op_sel_hi:[1,0,1]
	s_nop 1
	v_mov_b32_dpp v248, v144 row_ror:8 row_mask:0xf bank_mask:0xf
	v_mov_b32_dpp v249, v145 row_ror:8 row_mask:0xf bank_mask:0xf
	v_mov_b32_dpp v250, v146 row_ror:8 row_mask:0xf bank_mask:0xf
	v_mov_b32_dpp v251, v147 row_ror:8 row_mask:0xf bank_mask:0xf
	v_cndmask_b32_e64 v144, v248, v244, s[98:99]
	v_cndmask_b32_e64 v145, v249, v245, s[98:99]
	v_cndmask_b32_e64 v146, v250, v246, s[98:99]
	v_cndmask_b32_e64 v147, v251, v247, s[98:99]
	v_cndmask_b32_e64 v244, v244, v248, s[98:99]
	v_cndmask_b32_e64 v245, v245, v249, s[98:99]
	v_cndmask_b32_e64 v246, v246, v250, s[98:99]
	v_cndmask_b32_e64 v247, v247, v251, s[98:99]
	v_cndmask_b32_e64 v250, 1, 0, s[98:99]
	v_cndmask_b32_e64 v251, 0, 1, s[98:99]
	v_mul_i32_i24_e32 v248, s32, v250
	v_sub_u32_e32 v249, 0, v250
	v_lshl_add_u64 v[148:149], v[148:149], 0, v[248:249]
	global_store_dwordx4 v[148:149], v[144:147], off offset:512
	v_lshl_add_u32 v248, v251, 5, s101
	v_mov_b32_e32 v249, 0
	v_lshl_add_u64 v[148:149], v[148:149], 0, v[248:249]
	global_store_dwordx4 v[148:149], v[244:247], off offset:512
	v_mul_i32_i24_e32 v248, s100, v251
	v_sub_u32_e32 v249, 0, v251
	v_lshl_add_u64 v[148:149], v[148:149], 0, v[248:249]
	s_and_saveexec_b64 s[4:5], vcc
	s_xor_b64 s[4:5], exec, s[4:5]
	s_movk_i32 s6, 0xc490
	s_mov_b32 s7, -1
	v_lshl_add_u64 v[144:145], v[224:225], 0, s[6:7]
	s_or_saveexec_b64 s[4:5], s[4:5]
	v_mov_b64_e32 v[146:147], 0x2ae6000
	s_xor_b64 exec, exec, s[4:5]
	v_add_u32_e32 v144, 0x90, v224
	v_ashrrev_i32_e32 v145, 31, v144
	s_mov_b64 s[6:7], 0x4000
;     template <int PN> DI void body(AccRef acc, const Unit& u, int wr, int wc, int fr, int fq) const {
;     ...
;                     float* lo = orow(out, l, row, PN == 8 ? O_PSK : O_PSV, PN == 8 ? O_SSK : O_SSV, 256);
; #pragma unroll
;                     for (int bj = 0; bj < 2; ++bj) {
;                         *(f32x4*)(lo + bj * 128 + cl) = (f32x4){v[bj][0], v[bj][1], v[bj][2], v[bj][3]};
;                         *(f32x4*)(lo + bj * 128 + cl + 4) = (f32x4){v[bj][4], v[bj][5], v[bj][6], v[bj][7]};
;                     }
	v_lshl_add_u64 v[144:145], v[144:145], 0, s[6:7]
	v_mov_b64_e32 v[146:147], 0x1a00000
	s_or_b64 exec, exec, s[4:5]
	v_lshlrev_b32_e32 v146, 2, v146
	v_mov_b32_e32 v147, v225
	v_lshl_add_u64 v[146:147], s[84:85], 0, v[146:147]
	v_lshlrev_b64 v[144:145], 10, v[144:145]
	v_lshl_add_u64 v[144:145], v[146:147], 0, v[144:145]
	v_lshl_add_u64 v[148:149], v[198:199], 2, v[144:145]
	v_pk_fma_f32 v[146:147], v[46:47], v[170:171], v[142:143] op_sel_hi:[1,0,1]
	v_pk_fma_f32 v[144:145], v[44:45], v[170:171], v[140:141] op_sel_hi:[1,0,1]
	v_mov_b32_e32 v244, v144
	v_mov_b32_e32 v245, v145
	v_mov_b32_e32 v246, v146
	v_mov_b32_e32 v247, v147
	s_movk_i32 s4, 0x3fdf
	v_cmp_lt_i32_e32 vcc, s4, v164
	v_pk_fma_f32 v[146:147], v[42:43], v[170:171], v[138:139] op_sel_hi:[1,0,1]
	v_pk_fma_f32 v[144:145], v[40:41], v[170:171], v[136:137] op_sel_hi:[1,0,1]
	s_nop 1
	v_mov_b32_dpp v248, v144 row_ror:8 row_mask:0xf bank_mask:0xf
	v_mov_b32_dpp v249, v145 row_ror:8 row_mask:0xf bank_mask:0xf
	v_mov_b32_dpp v250, v146 row_ror:8 row_mask:0xf bank_mask:0xf
	v_mov_b32_dpp v251, v147 row_ror:8 row_mask:0xf bank_mask:0xf
	v_cndmask_b32_e64 v144, v248, v244, s[98:99]
	v_cndmask_b32_e64 v145, v249, v245, s[98:99]
	v_cndmask_b32_e64 v146, v250, v246, s[98:99]
	v_cndmask_b32_e64 v147, v251, v247, s[98:99]
	v_cndmask_b32_e64 v244, v244, v248, s[98:99]
	v_cndmask_b32_e64 v245, v245, v249, s[98:99]
	v_cndmask_b32_e64 v246, v246, v250, s[98:99]
	v_cndmask_b32_e64 v247, v247, v251, s[98:99]
	v_cndmask_b32_e64 v250, 1, 0, s[98:99]
	v_cndmask_b32_e64 v251, 0, 1, s[98:99]
	v_mul_i32_i24_e32 v248, s32, v250
	v_sub_u32_e32 v249, 0, v250
	v_lshl_add_u64 v[148:149], v[148:149], 0, v[248:249]
	global_store_dwordx4 v[148:149], v[144:147], off
	v_lshl_add_u32 v248, v251, 5, s101
	v_mov_b32_e32 v249, 0
	v_lshl_add_u64 v[148:149], v[148:149], 0, v[248:249]
	global_store_dwordx4 v[148:149], v[244:247], off
	v_mul_i32_i24_e32 v248, s100, v251
	v_sub_u32_e32 v249, 0, v251
	v_lshl_add_u64 v[148:149], v[148:149], 0, v[248:249]
	s_nop 1
	v_pk_fma_f32 v[146:147], v[38:39], v[170:171], v[134:135] op_sel_hi:[1,0,1]
	v_pk_fma_f32 v[144:145], v[36:37], v[170:171], v[132:133] op_sel_hi:[1,0,1]
	v_mov_b32_e32 v244, v144
	v_mov_b32_e32 v245, v145
	v_mov_b32_e32 v246, v146
	v_mov_b32_e32 v247, v147
	s_nop 1
	v_pk_fma_f32 v[146:147], v[30:31], v[170:171], v[130:131] op_sel_hi:[1,0,1]
	v_pk_fma_f32 v[144:145], v[28:29], v[170:171], v[128:129] op_sel_hi:[1,0,1]
	s_nop 1
	v_mov_b32_dpp v248, v144 row_ror:8 row_mask:0xf bank_mask:0xf
	v_mov_b32_dpp v249, v145 row_ror:8 row_mask:0xf bank_mask:0xf
	v_mov_b32_dpp v250, v146 row_ror:8 row_mask:0xf bank_mask:0xf
	v_mov_b32_dpp v251, v147 row_ror:8 row_mask:0xf bank_mask:0xf
	v_cndmask_b32_e64 v144, v248, v244, s[98:99]
	v_cndmask_b32_e64 v145, v249, v245, s[98:99]
	v_cndmask_b32_e64 v146, v250, v246, s[98:99]
	v_cndmask_b32_e64 v147, v251, v247, s[98:99]
	v_cndmask_b32_e64 v244, v244, v248, s[98:99]
	v_cndmask_b32_e64 v245, v245, v249, s[98:99]
	v_cndmask_b32_e64 v246, v246, v250, s[98:99]
	v_cndmask_b32_e64 v247, v247, v251, s[98:99]
	v_cndmask_b32_e64 v250, 1, 0, s[98:99]
	v_cndmask_b32_e64 v251, 0, 1, s[98:99]
	v_mul_i32_i24_e32 v248, s32, v250
	v_sub_u32_e32 v249, 0, v250
	v_lshl_add_u64 v[148:149], v[148:149], 0, v[248:249]
	global_store_dwordx4 v[148:149], v[144:147], off offset:512
	v_lshl_add_u32 v248, v251, 5, s101
	v_mov_b32_e32 v249, 0
	v_lshl_add_u64 v[148:149], v[148:149], 0, v[248:249]
	global_store_dwordx4 v[148:149], v[244:247], off offset:512
	v_mul_i32_i24_e32 v248, s100, v251
	v_sub_u32_e32 v249, 0, v251
	v_lshl_add_u64 v[148:149], v[148:149], 0, v[248:249]
	s_and_saveexec_b64 s[4:5], vcc
	s_xor_b64 s[4:5], exec, s[4:5]
	s_movk_i32 s6, 0xc4a0
	s_mov_b32 s7, -1
	v_lshl_add_u64 v[144:145], v[224:225], 0, s[6:7]
	s_or_saveexec_b64 s[4:5], s[4:5]
	v_mov_b64_e32 v[146:147], 0x2ae6000
	s_xor_b64 exec, exec, s[4:5]
	v_add_u32_e32 v144, 0xa0, v224
	v_ashrrev_i32_e32 v145, 31, v144
	s_mov_b64 s[6:7], 0x4000
	v_lshl_add_u64 v[144:145], v[144:145], 0, s[6:7]
	v_mov_b64_e32 v[146:147], 0x1a00000
	s_or_b64 exec, exec, s[4:5]
	v_lshlrev_b32_e32 v146, 2, v146
	v_mov_b32_e32 v147, v225
	v_lshl_add_u64 v[146:147], s[84:85], 0, v[146:147]
	v_lshlrev_b64 v[144:145], 10, v[144:145]
	v_lshl_add_u64 v[144:145], v[146:147], 0, v[144:145]
	v_lshl_add_u64 v[148:149], v[198:199], 2, v[144:145]
	v_pk_fma_f32 v[146:147], v[34:35], v[196:197], v[142:143] op_sel_hi:[1,0,1]
	v_pk_fma_f32 v[144:145], v[32:33], v[196:197], v[140:141] op_sel_hi:[1,0,1]
	v_mov_b32_e32 v244, v144
	v_mov_b32_e32 v245, v145
	v_mov_b32_e32 v246, v146
	v_mov_b32_e32 v247, v147
	s_movk_i32 s4, 0x3fcf
	v_cmp_lt_i32_e32 vcc, s4, v164
	v_pk_fma_f32 v[146:147], v[26:27], v[196:197], v[138:139] op_sel_hi:[1,0,1]
	v_pk_fma_f32 v[144:145], v[24:25], v[196:197], v[136:137] op_sel_hi:[1,0,1]
	s_nop 1
	v_mov_b32_dpp v248, v144 row_ror:8 row_mask:0xf bank_mask:0xf
	v_mov_b32_dpp v249, v145 row_ror:8 row_mask:0xf bank_mask:0xf
	v_mov_b32_dpp v250, v146 row_ror:8 row_mask:0xf bank_mask:0xf
	v_mov_b32_dpp v251, v147 row_ror:8 row_mask:0xf bank_mask:0xf
	v_cndmask_b32_e64 v144, v248, v244, s[98:99]
	v_cndmask_b32_e64 v145, v249, v245, s[98:99]
	v_cndmask_b32_e64 v146, v250, v246, s[98:99]
	v_cndmask_b32_e64 v147, v251, v247, s[98:99]
	v_cndmask_b32_e64 v244, v244, v248, s[98:99]
	v_cndmask_b32_e64 v245, v245, v249, s[98:99]
	v_cndmask_b32_e64 v246, v246, v250, s[98:99]
	v_cndmask_b32_e64 v247, v247, v251, s[98:99]
	v_cndmask_b32_e64 v250, 1, 0, s[98:99]
	v_cndmask_b32_e64 v251, 0, 1, s[98:99]
	v_mul_i32_i24_e32 v248, s32, v250
	v_sub_u32_e32 v249, 0, v250
	v_lshl_add_u64 v[148:149], v[148:149], 0, v[248:249]
;     template <int PN> DI void body(AccRef acc, const Unit& u, int wr, int wc, int fr, int fq) const {
;     ...
;                     float* lo = orow(out, l, row, PN == 8 ? O_PSK : O_PSV, PN == 8 ? O_SSK : O_SSV, 256);
; #pragma unroll
;                     for (int bj = 0; bj < 2; ++bj) {
;                         *(f32x4*)(lo + bj * 128 + cl) = (f32x4){v[bj][0], v[bj][1], v[bj][2], v[bj][3]};
;                         *(f32x4*)(lo + bj * 128 + cl + 4) = (f32x4){v[bj][4], v[bj][5], v[bj][6], v[bj][7]};
;                     }
	global_store_dwordx4 v[148:149], v[144:147], off
	v_lshl_add_u32 v248, v251, 5, s101
	v_mov_b32_e32 v249, 0
	v_lshl_add_u64 v[148:149], v[148:149], 0, v[248:249]
	global_store_dwordx4 v[148:149], v[244:247], off
	v_mul_i32_i24_e32 v248, s100, v251
	v_sub_u32_e32 v249, 0, v251
	v_lshl_add_u64 v[148:149], v[148:149], 0, v[248:249]
	s_nop 1
	v_pk_fma_f32 v[146:147], v[22:23], v[196:197], v[134:135] op_sel_hi:[1,0,1]
	v_pk_fma_f32 v[144:145], v[20:21], v[196:197], v[132:133] op_sel_hi:[1,0,1]
	v_mov_b32_e32 v244, v144
	v_mov_b32_e32 v245, v145
	v_mov_b32_e32 v246, v146
	v_mov_b32_e32 v247, v147
	s_nop 1
	v_pk_fma_f32 v[146:147], v[18:19], v[196:197], v[130:131] op_sel_hi:[1,0,1]
	v_pk_fma_f32 v[144:145], v[16:17], v[196:197], v[128:129] op_sel_hi:[1,0,1]
	s_nop 1
	v_mov_b32_dpp v248, v144 row_ror:8 row_mask:0xf bank_mask:0xf
	v_mov_b32_dpp v249, v145 row_ror:8 row_mask:0xf bank_mask:0xf
	v_mov_b32_dpp v250, v146 row_ror:8 row_mask:0xf bank_mask:0xf
	v_mov_b32_dpp v251, v147 row_ror:8 row_mask:0xf bank_mask:0xf
	v_cndmask_b32_e64 v144, v248, v244, s[98:99]
	v_cndmask_b32_e64 v145, v249, v245, s[98:99]
	v_cndmask_b32_e64 v146, v250, v246, s[98:99]
	v_cndmask_b32_e64 v147, v251, v247, s[98:99]
	v_cndmask_b32_e64 v244, v244, v248, s[98:99]
	v_cndmask_b32_e64 v245, v245, v249, s[98:99]
	v_cndmask_b32_e64 v246, v246, v250, s[98:99]
	v_cndmask_b32_e64 v247, v247, v251, s[98:99]
	v_cndmask_b32_e64 v250, 1, 0, s[98:99]
	v_cndmask_b32_e64 v251, 0, 1, s[98:99]
	v_mul_i32_i24_e32 v248, s32, v250
	v_sub_u32_e32 v249, 0, v250
	v_lshl_add_u64 v[148:149], v[148:149], 0, v[248:249]
	global_store_dwordx4 v[148:149], v[144:147], off offset:512
	v_lshl_add_u32 v248, v251, 5, s101
	v_mov_b32_e32 v249, 0
	v_lshl_add_u64 v[148:149], v[148:149], 0, v[248:249]
	global_store_dwordx4 v[148:149], v[244:247], off offset:512
	v_mul_i32_i24_e32 v248, s100, v251
	v_sub_u32_e32 v249, 0, v251
	v_lshl_add_u64 v[148:149], v[148:149], 0, v[248:249]
	s_and_saveexec_b64 s[4:5], vcc
	s_xor_b64 s[4:5], exec, s[4:5]
	s_movk_i32 s6, 0xc4b0
	s_mov_b32 s7, -1
	v_lshl_add_u64 v[144:145], v[224:225], 0, s[6:7]
	s_or_saveexec_b64 s[4:5], s[4:5]
	v_mov_b64_e32 v[146:147], 0x2ae6000
	s_xor_b64 exec, exec, s[4:5]
	v_add_u32_e32 v144, 0xb0, v224
	v_ashrrev_i32_e32 v145, 31, v144
	s_mov_b64 s[6:7], 0x4000
	v_lshl_add_u64 v[144:145], v[144:145], 0, s[6:7]
	v_mov_b64_e32 v[146:147], 0x1a00000
	s_or_b64 exec, exec, s[4:5]
	v_lshlrev_b32_e32 v224, 2, v146
	v_lshl_add_u64 v[146:147], s[84:85], 0, v[224:225]
	v_lshlrev_b64 v[144:145], 10, v[144:145]
	v_lshl_add_u64 v[144:145], v[146:147], 0, v[144:145]
	v_lshl_add_u64 v[144:145], v[198:199], 2, v[144:145]
	v_pk_fma_f32 v[142:143], v[14:15], v[194:195], v[142:143] op_sel_hi:[1,0,1]
	v_pk_fma_f32 v[140:141], v[12:13], v[194:195], v[140:141] op_sel_hi:[1,0,1]
	v_pk_fma_f32 v[138:139], v[10:11], v[194:195], v[138:139] op_sel_hi:[1,0,1]
	v_pk_fma_f32 v[136:137], v[8:9], v[194:195], v[136:137] op_sel_hi:[1,0,1]
	v_pk_fma_f32 v[134:135], v[6:7], v[194:195], v[134:135] op_sel_hi:[1,0,1]
	v_pk_fma_f32 v[132:133], v[4:5], v[194:195], v[132:133] op_sel_hi:[1,0,1]
	v_pk_fma_f32 v[130:131], v[2:3], v[194:195], v[130:131] op_sel_hi:[1,0,1]
	v_pk_fma_f32 v[128:129], v[0:1], v[194:195], v[128:129] op_sel_hi:[1,0,1]
	s_mov_b64 s[80:81], 0
	v_mov_b32_e32 v244, v140
	v_mov_b32_e32 v245, v141
	v_mov_b32_e32 v246, v142
	v_mov_b32_e32 v247, v143
	s_nop 1
	v_mov_b32_dpp v248, v136 row_ror:8 row_mask:0xf bank_mask:0xf
	v_mov_b32_dpp v249, v137 row_ror:8 row_mask:0xf bank_mask:0xf
	v_mov_b32_dpp v250, v138 row_ror:8 row_mask:0xf bank_mask:0xf
	v_mov_b32_dpp v251, v139 row_ror:8 row_mask:0xf bank_mask:0xf
	v_cndmask_b32_e64 v136, v248, v244, s[98:99]
	v_cndmask_b32_e64 v137, v249, v245, s[98:99]
	v_cndmask_b32_e64 v138, v250, v246, s[98:99]
	v_cndmask_b32_e64 v139, v251, v247, s[98:99]
	v_cndmask_b32_e64 v244, v244, v248, s[98:99]
	v_cndmask_b32_e64 v245, v245, v249, s[98:99]
	v_cndmask_b32_e64 v246, v246, v250, s[98:99]
	v_cndmask_b32_e64 v247, v247, v251, s[98:99]
	v_cndmask_b32_e64 v250, 1, 0, s[98:99]
	v_cndmask_b32_e64 v251, 0, 1, s[98:99]
	v_mul_i32_i24_e32 v248, s32, v250
	v_sub_u32_e32 v249, 0, v250
	v_lshl_add_u64 v[144:145], v[144:145], 0, v[248:249]
	global_store_dwordx4 v[144:145], v[136:139], off
	v_lshl_add_u32 v248, v251, 5, s101
	v_mov_b32_e32 v249, 0
	v_lshl_add_u64 v[144:145], v[144:145], 0, v[248:249]
	global_store_dwordx4 v[144:145], v[244:247], off
	v_mul_i32_i24_e32 v248, s100, v251
	v_sub_u32_e32 v249, 0, v251
	v_lshl_add_u64 v[144:145], v[144:145], 0, v[248:249]
	v_mov_b32_e32 v244, v132
	v_mov_b32_e32 v245, v133
	v_mov_b32_e32 v246, v134
	v_mov_b32_e32 v247, v135
	s_nop 1
	v_mov_b32_dpp v248, v128 row_ror:8 row_mask:0xf bank_mask:0xf
	v_mov_b32_dpp v249, v129 row_ror:8 row_mask:0xf bank_mask:0xf
	v_mov_b32_dpp v250, v130 row_ror:8 row_mask:0xf bank_mask:0xf
	v_mov_b32_dpp v251, v131 row_ror:8 row_mask:0xf bank_mask:0xf
	v_cndmask_b32_e64 v128, v248, v244, s[98:99]
	v_cndmask_b32_e64 v129, v249, v245, s[98:99]
	v_cndmask_b32_e64 v130, v250, v246, s[98:99]
	v_cndmask_b32_e64 v131, v251, v247, s[98:99]
	v_cndmask_b32_e64 v244, v244, v248, s[98:99]
	v_cndmask_b32_e64 v245, v245, v249, s[98:99]
	v_cndmask_b32_e64 v246, v246, v250, s[98:99]
	v_cndmask_b32_e64 v247, v247, v251, s[98:99]
	v_cndmask_b32_e64 v250, 1, 0, s[98:99]
	v_cndmask_b32_e64 v251, 0, 1, s[98:99]
	v_mul_i32_i24_e32 v248, s32, v250
	v_sub_u32_e32 v249, 0, v250
	v_lshl_add_u64 v[144:145], v[144:145], 0, v[248:249]
	global_store_dwordx4 v[144:145], v[128:131], off offset:512
	v_lshl_add_u32 v248, v251, 5, s101
	v_mov_b32_e32 v249, 0
	v_lshl_add_u64 v[144:145], v[144:145], 0, v[248:249]
	global_store_dwordx4 v[144:145], v[244:247], off offset:512
	v_mul_i32_i24_e32 v248, s100, v251
	v_sub_u32_e32 v249, 0, v251
	v_lshl_add_u64 v[144:145], v[144:145], 0, v[248:249]

; DI float sum16(const float* p) { const f32x4* q = (const f32x4*)p; f32x4 a = q[0], b = q[1], c = q[2], d = q[3]; f32x4 s = (a + b) + (c + d); return (s[0] + s[1]) + (s[2] + s[3]); }
;     template <int PN> DI void body(AccRef acc, const Unit& u, int wr, int wc, int fr, int fq) const {
;     ...
;         for (int ai = 0; ai < 2; ++ai) {
;             const int rb_ = u.pm * 256 + ai * 128 + wr * 64 + fr;
; #pragma unroll
;             for (int m = 0; m < 4; ++m) rinvh[ai][m] = rsqrtf(sum16(ssq + (size_t)(rb_ + 16 * m + zdep) * 16) * (1.f / 1024.f) + EPS);
;             asm volatile("v_mov_b32 %0, 0" : "=v"(zdep) : "v"(rinvh[ai][0]), "v"(rinvh[ai][1]), "v"(rinvh[ai][2]), "v"(rinvh[ai][3]));
;         }
; #pragma unroll
;         for (int ai = 0; ai < 2; ++ai) {
;             const int rb_ = u.pm * 256 + ai * 128 + wr * 64 + fr;
;             int mb_, p_, k_; row_info(rb_, mb_, p_, k_);
; #pragma unroll
;             for (int bj = 0; bj < 2; ++bj)
; #pragma unroll
;                 for (int n = 0; n < 2; ++n) cvh[ai][bj][n] = *(const f32x4*)(cv + (size_t)(mb_ + zdep) * NIN + PN * 256 + bj * 128 + cl + 4 * n);
;         }
;     DI void operator()(AccRef acc, const Unit& u, int wr, int wc, int fr, int fq) const {
;         switch (u.pn) {
;             case 0: body<0>(acc, u, wr, wc, fr, fq); break;
;             case 1: body<1>(acc, u, wr, wc, fr, fq); break;
;             case 2: body<2>(acc, u, wr, wc, fr, fq); break;
;             case 3: body<3>(acc, u, wr, wc, fr, fq); break;
;             case 4: body<4>(acc, u, wr, wc, fr, fq); break;
;             case 5: body<5>(acc, u, wr, wc, fr, fq); break;
;             case 6: body<6>(acc, u, wr, wc, fr, fq); break;
;             case 7: body<7>(acc, u, wr, wc, fr, fq); break;
;             case 8: body<8>(acc, u, wr, wc, fr, fq); break;
;             default: body<9>(acc, u, wr, wc, fr, fq); break;
;         }
.LBB0_1878:
	v_readlane_b32 s2, v253, 32
	v_mbcnt_lo_u32_b32 v128, -1, 0
	v_mbcnt_hi_u32_b32 v128, -1, v128
	s_mov_b32 s60, s39
	v_and_b32_e32 v214, 15, v128
	v_bfe_u32 v213, v128, 4, 2
	s_mov_b32 s43, s29
	s_lshl_b32 s22, s43, 6
	s_lshl_b32 s23, s34, 8
	s_add_i32 s22, s22, s23
	v_add_u32_e32 v244, s22, v214
	v_lshlrev_b32_e32 v244, 6, v244
	v_lshl_add_u32 v244, v213, 4, v244
	global_load_dwordx4 v[228:231], v244, s[70:71]
	global_load_dwordx4 v[232:235], v244, s[70:71] offset:1024
	global_load_dwordx4 v[236:239], v244, s[70:71] offset:2048
	global_load_dwordx4 v[240:243], v244, s[70:71] offset:3072
	v_add_u32_e32 v244, 0x2000, v244
	global_load_dwordx4 v[216:219], v244, s[70:71]
	global_load_dwordx4 v[220:223], v244, s[70:71] offset:1024
	global_load_dwordx4 v[142:145], v244, s[70:71] offset:2048
	global_load_dwordx4 v[146:149], v244, s[70:71] offset:3072
	v_mov_b32_e32 v245, 0x3a800000
	s_waitcnt vmcnt(4)
	v_pk_add_f32 v[228:229], v[228:229], v[230:231]
	v_pk_add_f32 v[232:233], v[232:233], v[234:235]
	v_pk_add_f32 v[236:237], v[236:237], v[238:239]
	v_pk_add_f32 v[240:241], v[240:241], v[242:243]
	v_add_f32_e32 v228, v228, v229
	v_add_f32_e32 v232, v232, v233
	v_add_f32_e32 v236, v236, v237
	v_add_f32_e32 v240, v240, v241
	v_mov_b32_e32 v229, v228
	v_mov_b32_e32 v233, v232
	v_mov_b32_e32 v237, v236
	v_mov_b32_e32 v241, v240
	s_waitcnt vmcnt(0)
	v_pk_add_f32 v[216:217], v[216:217], v[218:219]
	v_pk_add_f32 v[220:221], v[220:221], v[222:223]
	v_pk_add_f32 v[142:143], v[142:143], v[144:145]
	v_pk_add_f32 v[146:147], v[146:147], v[148:149]
	v_add_f32_e32 v216, v216, v217
	v_add_f32_e32 v220, v220, v221
	v_add_f32_e32 v142, v142, v143
	v_add_f32_e32 v146, v146, v147
	v_mov_b32_e32 v217, v216
	v_mov_b32_e32 v221, v220
	v_mov_b32_e32 v143, v142
	v_mov_b32_e32 v147, v146
	s_nop 1
	v_permlane32_swap_b32_e32 v228, v229
	v_permlane32_swap_b32_e32 v232, v233
	v_permlane32_swap_b32_e32 v236, v237
	v_permlane32_swap_b32_e32 v240, v241
	v_permlane32_swap_b32_e32 v216, v217
	v_permlane32_swap_b32_e32 v220, v221
	v_permlane32_swap_b32_e32 v142, v143
	v_permlane32_swap_b32_e32 v146, v147
	v_add_f32_e32 v228, v228, v229
	v_add_f32_e32 v232, v232, v233
	v_add_f32_e32 v236, v236, v237
	v_add_f32_e32 v240, v240, v241
	v_add_f32_e32 v216, v216, v217
	v_add_f32_e32 v220, v220, v221
	v_add_f32_e32 v142, v142, v143
	v_add_f32_e32 v146, v146, v147
	v_mov_b32_e32 v229, v228
	v_mov_b32_e32 v233, v232
	v_mov_b32_e32 v237, v236
	v_mov_b32_e32 v241, v240
	v_mov_b32_e32 v217, v216
	v_mov_b32_e32 v221, v220
	v_mov_b32_e32 v143, v142
	v_mov_b32_e32 v147, v146
	s_nop 1
	v_permlane16_swap_b32_e32 v228, v229
	v_permlane16_swap_b32_e32 v232, v233
	v_permlane16_swap_b32_e32 v236, v237
	v_permlane16_swap_b32_e32 v240, v241
	v_permlane16_swap_b32_e32 v216, v217
	v_permlane16_swap_b32_e32 v220, v221
	v_permlane16_swap_b32_e32 v142, v143
	v_permlane16_swap_b32_e32 v146, v147
	v_add_f32_e32 v228, v228, v229
	v_add_f32_e32 v232, v232, v233
	v_add_f32_e32 v236, v236, v237
	v_add_f32_e32 v240, v240, v241
	v_add_f32_e32 v216, v216, v217
	v_add_f32_e32 v220, v220, v221
	v_add_f32_e32 v142, v142, v143
	v_add_f32_e32 v146, v146, v147
	v_fmaak_f32 v228, v245, v228, 0x358637bd
	v_fmaak_f32 v232, v245, v232, 0x358637bd
	v_fmaak_f32 v236, v245, v236, 0x358637bd
	v_fmaak_f32 v240, v245, v240, 0x358637bd
	v_fmaak_f32 v216, v245, v216, 0x358637bd
	v_fmaak_f32 v220, v245, v220, 0x358637bd
	v_fmaak_f32 v142, v245, v142, 0x358637bd
	v_fmaak_f32 v146, v245, v146, 0x358637bd
	v_rsq_f32_e32 v244, v228
	v_rsq_f32_e32 v245, v232
	v_rsq_f32_e32 v246, v236
	v_rsq_f32_e32 v247, v240
	v_rsq_f32_e32 v248, v216
	v_rsq_f32_e32 v249, v220
	v_rsq_f32_e32 v250, v142
	v_rsq_f32_e32 v251, v146
	s_mov_b64 s[2:3], -1
	s_mov_b64 s[8:9], 0
	s_cmp_lt_i32 s66, 4
	s_mov_b64 s[80:81], 0
	s_cbranch_scc1 .LBB0_1913
	s_cmp_gt_i32 s66, 5
	s_cbranch_scc0 .LBB0_1907
	s_cmp_gt_i32 s66, 6
	s_cbranch_scc0 .LBB0_1904
	s_cmp_gt_i32 s66, 7
	s_cbranch_scc0 .LBB0_1901
	s_cmp_eq_u32 s66, 8
	s_mov_b64 s[80:81], -1
	s_cbranch_scc0 .LBB0_1900
	s_lshl_b32 s2, s43, 6
	s_lshl_b32 s3, s34, 8
	s_add_i32 s2, s2, s3
	v_add_u32_e32 v160, s2, v214
	v_ashrrev_i32_e32 v161, 31, v160
	v_lshlrev_b64 v[128:129], 6, v[160:161]
	v_lshl_add_u64 v[140:141], s[70:71], 0, v[128:129]
	s_nop 0
	v_add_u32_e32 v190, 16, v160
	v_ashrrev_i32_e32 v191, 31, v190
	s_mov_b32 s2, 0x358637bd
	s_mov_b32 s4, 0x3a800000
	v_add_u32_e32 v166, 32, v160
	v_ashrrev_i32_e32 v167, 31, v166
	v_add_u32_e32 v168, 48, v160
	v_ashrrev_i32_e32 v169, 31, v168
	v_add_u32_e32 v164, 0x80, v160
	s_movk_i32 s6, 0x2800
	s_mov_b64 s[12:13], 0x126000
	s_mov_b32 s7, 0x126000
	v_add_u32_e32 v163, 0xffffc080, v160
	v_mov_b32_e32 v165, 0xffffc400
	v_mov_b32_e32 v171, 0x4000
	s_nop 0
	v_lshlrev_b64 v[128:129], 6, v[190:191]
	v_lshl_add_u64 v[140:141], s[70:71], 0, v[128:129]
	s_nop 0
	s_nop 0
	v_mov_b64_e32 v[128:129], s[2:3]
	s_nop 0
	s_nop 0
	s_nop 0
	v_mov_b32_e32 v192, v244
	s_nop 0
	v_mov_b32_e32 v162, v245
	v_lshlrev_b64 v[130:131], 6, v[166:167]
	v_lshl_add_u64 v[142:143], s[70:71], 0, v[130:131]
	s_nop 0
	s_nop 0
	v_lshlrev_b64 v[130:131], 6, v[168:169]
	v_lshl_add_u64 v[142:143], s[70:71], 0, v[130:131]
	s_nop 0
	s_nop 0
	s_nop 0
	s_nop 0
	s_nop 0
	s_nop 0
	v_mov_b32_e32 v172, v246
	s_nop 0
	v_mov_b32_e32 v188, v247
	v_mov_b32 v130, 0
	s_nop 0
	v_add_u32_e32 v130, v130, v164
	v_ashrrev_i32_e32 v131, 31, v130
	v_lshlrev_b64 v[132:133], 6, v[130:131]
	v_lshl_add_u64 v[144:145], s[70:71], 0, v[132:133]
	s_nop 0
	s_nop 0
	v_add_u32_e32 v132, 16, v130
	v_ashrrev_i32_e32 v133, 31, v132
	v_lshlrev_b64 v[132:133], 6, v[132:133]
	v_lshl_add_u64 v[144:145], s[70:71], 0, v[132:133]
	s_nop 0
	s_nop 0
;     template <int PN> DI void body(AccRef acc, const Unit& u, int wr, int wc, int fr, int fq) const {
;     ...
;                     float* lo = orow(out, l, row, PN == 8 ? O_PSK : O_PSV, PN == 8 ? O_SSK : O_SSV, 256);
; #pragma unroll
;                     for (int bj = 0; bj < 2; ++bj) {
;                         *(f32x4*)(lo + bj * 128 + cl) = (f32x4){v[bj][0], v[bj][1], v[bj][2], v[bj][3]};
;                         *(f32x4*)(lo + bj * 128 + cl + 4) = (f32x4){v[bj][4], v[bj][5], v[bj][6], v[bj][7]};
;                     }
	s_nop 0
	s_nop 0
	s_nop 0
	s_nop 0
	v_mov_b32_e32 v174, v248
	s_nop 0
	v_mov_b32_e32 v170, v249
	v_add_u32_e32 v132, 32, v130
	v_ashrrev_i32_e32 v133, 31, v132
	v_lshlrev_b64 v[132:133], 6, v[132:133]
	v_lshl_add_u64 v[144:145], s[70:71], 0, v[132:133]
	s_nop 0
	v_add_u32_e32 v130, 48, v130
	v_ashrrev_i32_e32 v131, 31, v130
	v_lshlrev_b64 v[130:131], 6, v[130:131]
	v_lshl_add_u64 v[142:143], s[70:71], 0, v[130:131]
	s_nop 0
	s_nop 0
	s_nop 0
	s_nop 0
	s_nop 0
	s_nop 0
	v_mov_b32_e32 v196, v250
	s_lshl_b32 s2, s60, 5
	v_lshl_add_u32 v198, v213, 3, s2
	v_cmp_gt_i32_e64 s[2:3], s94, v160
	v_mov_b32_e32 v194, v251
	v_add_u32_e32 v129, 0xffffc000, v160
	v_lshrrev_b32_e32 v129, 6, v129
	v_ashrrev_i32_e32 v128, 11, v160
	v_add_u32_e32 v129, 8, v129
	v_cndmask_b32_e64 v128, v129, v128, s[2:3]
	v_mov_b32 v134, 0
	v_ashrrev_i32_e32 v199, 31, v198
	v_add_u32_e32 v130, v134, v128
	v_mov_b64_e32 v[128:129], s[74:75]
	v_mad_i64_i32 v[130:131], s[4:5], v130, s6, v[128:129]
	v_lshlrev_b64 v[200:201], 2, v[198:199]
	v_lshl_add_u64 v[130:131], v[130:131], 0, v[200:201]
	v_lshl_add_u64 v[132:133], v[130:131], 0, s[12:13]
	v_add_co_u32_e32 v130, vcc, s7, v130
	s_movk_i32 s4, 0x3fff
	s_nop 0
	v_addc_co_u32_e32 v131, vcc, 0, v131, vcc
	global_load_dwordx4 v[152:155], v[130:131], off
	global_load_dwordx4 v[156:159], v[132:133], off offset:16
	global_load_dwordx4 v[144:147], v[132:133], off offset:528
	global_load_dwordx4 v[148:151], v[132:133], off offset:512
	v_lshrrev_b32_e32 v131, 6, v163
	v_cmp_lt_i32_e32 vcc, s4, v164
	v_cmp_gt_i32_e64 s[4:5], s94, v164
	v_ashrrev_i32_e32 v130, 11, v164
	v_add_u32_e32 v131, 8, v131
	v_cndmask_b32_e64 v130, v131, v130, s[4:5]
	v_add_u32_e32 v130, v134, v130
	v_mad_i64_i32 v[128:129], s[4:5], v130, s6, v[128:129]
	v_lshl_add_u64 v[128:129], v[128:129], 0, v[200:201]
	v_lshl_add_u64 v[132:133], v[128:129], 0, s[12:13]
	v_add_co_u32_e64 v128, s[4:5], s7, v128
	v_cndmask_b32_e64 v203, -1, 0, s[2:3]
	s_nop 0
	v_addc_co_u32_e64 v129, s[4:5], 0, v129, s[4:5]
	global_load_dwordx4 v[140:143], v[128:129], off
	global_load_dwordx4 v[136:139], v[132:133], off offset:16
	s_nop 0
	global_load_dwordx4 v[128:131], v[132:133], off offset:528
	s_nop 0
	global_load_dwordx4 v[132:135], v[132:133], off offset:512
	v_cndmask_b32_e64 v202, v165, v171, s[2:3]
	v_mov_b32_e32 v165, 0xab98000
	v_mov_b32_e32 v171, 0x6800000
	v_lshl_add_u64 v[202:203], v[202:203], 0, v[160:161]
	v_cndmask_b32_e64 v224, v165, v171, s[2:3]
	v_lshl_add_u64 v[204:205], s[84:85], 0, v[224:225]
	v_lshlrev_b64 v[202:203], 10, v[202:203]
	v_lshl_add_u64 v[202:203], v[204:205], 0, v[202:203]
	v_lshl_add_u64 v[206:207], v[202:203], 0, v[200:201]
	s_movk_i32 s4, 0xc410
	v_mov_b32_e32 v224, v160
	s_mov_b32 s5, -1
	v_cmp_gt_i32_e64 s[2:3], s82, v160
	s_movk_i32 s6, 0xc420
	s_mov_b32 s7, -1
	s_waitcnt vmcnt(7)
	v_pk_fma_f32 v[204:205], v[126:127], v[192:193], v[154:155] op_sel_hi:[1,0,1]
	v_pk_fma_f32 v[202:203], v[124:125], v[192:193], v[152:153] op_sel_hi:[1,0,1]
	s_mov_b32 s98, 0xff00ff
	s_mov_b32 s99, 0xff00ff
	s_mov_b32 s32, 0xffffe010
	s_mov_b32 s100, 0xffffdff0
	s_movk_i32 s101, 0x1ff0
	v_mov_b32_e32 v244, v202
	v_mov_b32_e32 v245, v203
	v_mov_b32_e32 v246, v204
	v_mov_b32_e32 v247, v205
	s_waitcnt vmcnt(6)
	s_nop 0
	v_pk_fma_f32 v[204:205], v[122:123], v[192:193], v[158:159] op_sel_hi:[1,0,1]
	v_pk_fma_f32 v[202:203], v[120:121], v[192:193], v[156:157] op_sel_hi:[1,0,1]
	s_nop 1
	v_mov_b32_dpp v248, v202 row_ror:8 row_mask:0xf bank_mask:0xf
	v_mov_b32_dpp v249, v203 row_ror:8 row_mask:0xf bank_mask:0xf
	v_mov_b32_dpp v250, v204 row_ror:8 row_mask:0xf bank_mask:0xf
	v_mov_b32_dpp v251, v205 row_ror:8 row_mask:0xf bank_mask:0xf
	v_cndmask_b32_e64 v202, v248, v244, s[98:99]
	v_cndmask_b32_e64 v203, v249, v245, s[98:99]
	v_cndmask_b32_e64 v204, v250, v246, s[98:99]
	v_cndmask_b32_e64 v205, v251, v247, s[98:99]
	v_cndmask_b32_e64 v244, v244, v248, s[98:99]
	v_cndmask_b32_e64 v245, v245, v249, s[98:99]
	v_cndmask_b32_e64 v246, v246, v250, s[98:99]
	v_cndmask_b32_e64 v247, v247, v251, s[98:99]
	v_cndmask_b32_e64 v250, 1, 0, s[98:99]
	v_cndmask_b32_e64 v251, 0, 1, s[98:99]
	v_mul_i32_i24_e32 v248, s32, v250
	v_sub_u32_e32 v249, 0, v250
	v_lshl_add_u64 v[206:207], v[206:207], 0, v[248:249]
	global_store_dwordx4 v[206:207], v[202:205], off
	v_lshl_add_u32 v248, v251, 5, s101
	v_mov_b32_e32 v249, 0
	v_lshl_add_u64 v[206:207], v[206:207], 0, v[248:249]
	global_store_dwordx4 v[206:207], v[244:247], off
	v_mul_i32_i24_e32 v248, s100, v251
	v_sub_u32_e32 v249, 0, v251
	v_lshl_add_u64 v[206:207], v[206:207], 0, v[248:249]
	s_waitcnt vmcnt(5)
;     template <int PN> DI void body(AccRef acc, const Unit& u, int wr, int wc, int fr, int fq) const {
;     ...
;                     float* lo = orow(out, l, row, PN == 8 ? O_PSK : O_PSV, PN == 8 ? O_SSK : O_SSV, 256);
; #pragma unroll
;                     for (int bj = 0; bj < 2; ++bj) {
;                         *(f32x4*)(lo + bj * 128 + cl) = (f32x4){v[bj][0], v[bj][1], v[bj][2], v[bj][3]};
;                         *(f32x4*)(lo + bj * 128 + cl + 4) = (f32x4){v[bj][4], v[bj][5], v[bj][6], v[bj][7]};
;                     }
	s_nop 0
	v_pk_fma_f32 v[204:205], v[118:119], v[192:193], v[150:151] op_sel_hi:[1,0,1]
	v_pk_fma_f32 v[202:203], v[116:117], v[192:193], v[148:149] op_sel_hi:[1,0,1]
	v_mov_b32_e32 v244, v202
	v_mov_b32_e32 v245, v203
	v_mov_b32_e32 v246, v204
	v_mov_b32_e32 v247, v205
	s_nop 1
	v_pk_fma_f32 v[204:205], v[114:115], v[192:193], v[146:147] op_sel_hi:[1,0,1]
	v_pk_fma_f32 v[202:203], v[112:113], v[192:193], v[144:145] op_sel_hi:[1,0,1]
	v_lshl_add_u64 v[192:193], v[224:225], 0, s[4:5]
	s_mov_b64 s[4:5], 0x4000
	v_lshl_add_u64 v[190:191], v[190:191], 0, s[4:5]
	v_cndmask_b32_e64 v191, v193, v191, s[2:3]
	v_cndmask_b32_e64 v190, v192, v190, s[2:3]
	v_cndmask_b32_e64 v192, v165, v171, s[2:3]
	v_mov_b32_e32 v193, v225
	v_lshl_add_u64 v[192:193], s[84:85], 0, v[192:193]
	v_lshlrev_b64 v[190:191], 10, v[190:191]
	v_lshl_add_u64 v[190:191], v[192:193], 0, v[190:191]
	s_nop 1
	v_mov_b32_dpp v248, v202 row_ror:8 row_mask:0xf bank_mask:0xf
	v_mov_b32_dpp v249, v203 row_ror:8 row_mask:0xf bank_mask:0xf
	v_mov_b32_dpp v250, v204 row_ror:8 row_mask:0xf bank_mask:0xf
	v_mov_b32_dpp v251, v205 row_ror:8 row_mask:0xf bank_mask:0xf
	v_cndmask_b32_e64 v202, v248, v244, s[98:99]
	v_cndmask_b32_e64 v203, v249, v245, s[98:99]
	v_cndmask_b32_e64 v204, v250, v246, s[98:99]
	v_cndmask_b32_e64 v205, v251, v247, s[98:99]
	v_cndmask_b32_e64 v244, v244, v248, s[98:99]
	v_cndmask_b32_e64 v245, v245, v249, s[98:99]
	v_cndmask_b32_e64 v246, v246, v250, s[98:99]
	v_cndmask_b32_e64 v247, v247, v251, s[98:99]
	v_cndmask_b32_e64 v250, 1, 0, s[98:99]
	v_cndmask_b32_e64 v251, 0, 1, s[98:99]
	v_mul_i32_i24_e32 v248, s32, v250
	v_sub_u32_e32 v249, 0, v250
	v_lshl_add_u64 v[206:207], v[206:207], 0, v[248:249]
	global_store_dwordx4 v[206:207], v[202:205], off offset:512
	v_lshl_add_u32 v248, v251, 5, s101
	v_mov_b32_e32 v249, 0
	v_lshl_add_u64 v[206:207], v[206:207], 0, v[248:249]
	global_store_dwordx4 v[206:207], v[244:247], off offset:512
	v_mul_i32_i24_e32 v248, s100, v251
	v_sub_u32_e32 v249, 0, v251
	v_lshl_add_u64 v[206:207], v[206:207], 0, v[248:249]
	v_pk_fma_f32 v[192:193], v[110:111], v[162:163], v[154:155] op_sel_hi:[1,0,1]
	v_cmp_gt_i32_e64 s[2:3], s83, v160
	v_lshl_add_u64 v[202:203], v[190:191], 0, v[200:201]
	v_pk_fma_f32 v[190:191], v[108:109], v[162:163], v[152:153] op_sel_hi:[1,0,1]
	v_mov_b32_e32 v244, v190
	v_mov_b32_e32 v245, v191
	v_mov_b32_e32 v246, v192
	v_mov_b32_e32 v247, v193
	v_lshl_add_u64 v[166:167], v[166:167], 0, s[4:5]
	s_nop 0
	v_pk_fma_f32 v[192:193], v[106:107], v[162:163], v[158:159] op_sel_hi:[1,0,1]
	v_pk_fma_f32 v[190:191], v[104:105], v[162:163], v[156:157] op_sel_hi:[1,0,1]
	s_nop 1
	v_mov_b32_dpp v248, v190 row_ror:8 row_mask:0xf bank_mask:0xf
	v_mov_b32_dpp v249, v191 row_ror:8 row_mask:0xf bank_mask:0xf
	v_mov_b32_dpp v250, v192 row_ror:8 row_mask:0xf bank_mask:0xf
	v_mov_b32_dpp v251, v193 row_ror:8 row_mask:0xf bank_mask:0xf
	v_cndmask_b32_e64 v190, v248, v244, s[98:99]
	v_cndmask_b32_e64 v191, v249, v245, s[98:99]
	v_cndmask_b32_e64 v192, v250, v246, s[98:99]
	v_cndmask_b32_e64 v193, v251, v247, s[98:99]
	v_cndmask_b32_e64 v244, v244, v248, s[98:99]
	v_cndmask_b32_e64 v245, v245, v249, s[98:99]
	v_cndmask_b32_e64 v246, v246, v250, s[98:99]
	v_cndmask_b32_e64 v247, v247, v251, s[98:99]
	v_cndmask_b32_e64 v250, 1, 0, s[98:99]
	v_cndmask_b32_e64 v251, 0, 1, s[98:99]
	v_mul_i32_i24_e32 v248, s32, v250
	v_sub_u32_e32 v249, 0, v250
	v_lshl_add_u64 v[202:203], v[202:203], 0, v[248:249]
	global_store_dwordx4 v[202:203], v[190:193], off
	v_lshl_add_u32 v248, v251, 5, s101
	v_mov_b32_e32 v249, 0
	v_lshl_add_u64 v[202:203], v[202:203], 0, v[248:249]
	global_store_dwordx4 v[202:203], v[244:247], off
	v_mul_i32_i24_e32 v248, s100, v251
	v_sub_u32_e32 v249, 0, v251
	v_lshl_add_u64 v[202:203], v[202:203], 0, v[248:249]
	s_nop 1
	v_pk_fma_f32 v[192:193], v[102:103], v[162:163], v[150:151] op_sel_hi:[1,0,1]
	v_pk_fma_f32 v[190:191], v[100:101], v[162:163], v[148:149] op_sel_hi:[1,0,1]
	v_mov_b32_e32 v244, v190
	v_mov_b32_e32 v245, v191
	v_mov_b32_e32 v246, v192
	v_mov_b32_e32 v247, v193
	s_nop 1
	v_pk_fma_f32 v[192:193], v[98:99], v[162:163], v[146:147] op_sel_hi:[1,0,1]
	v_pk_fma_f32 v[190:191], v[96:97], v[162:163], v[144:145] op_sel_hi:[1,0,1]
	s_nop 1
	v_mov_b32_dpp v248, v190 row_ror:8 row_mask:0xf bank_mask:0xf
	v_mov_b32_dpp v249, v191 row_ror:8 row_mask:0xf bank_mask:0xf
	v_mov_b32_dpp v250, v192 row_ror:8 row_mask:0xf bank_mask:0xf
	v_mov_b32_dpp v251, v193 row_ror:8 row_mask:0xf bank_mask:0xf
	v_cndmask_b32_e64 v190, v248, v244, s[98:99]
	v_cndmask_b32_e64 v191, v249, v245, s[98:99]
	v_cndmask_b32_e64 v192, v250, v246, s[98:99]
	v_cndmask_b32_e64 v193, v251, v247, s[98:99]
	v_cndmask_b32_e64 v244, v244, v248, s[98:99]
	v_cndmask_b32_e64 v245, v245, v249, s[98:99]
	v_cndmask_b32_e64 v246, v246, v250, s[98:99]
	v_cndmask_b32_e64 v247, v247, v251, s[98:99]
	v_cndmask_b32_e64 v250, 1, 0, s[98:99]
	v_cndmask_b32_e64 v251, 0, 1, s[98:99]
	v_mul_i32_i24_e32 v248, s32, v250
	v_sub_u32_e32 v249, 0, v250
	v_lshl_add_u64 v[202:203], v[202:203], 0, v[248:249]
	global_store_dwordx4 v[202:203], v[190:193], off offset:512
	v_lshl_add_u32 v248, v251, 5, s101
	v_mov_b32_e32 v249, 0
	v_lshl_add_u64 v[202:203], v[202:203], 0, v[248:249]
	global_store_dwordx4 v[202:203], v[244:247], off offset:512
	v_mul_i32_i24_e32 v248, s100, v251
	v_sub_u32_e32 v249, 0, v251
	v_lshl_add_u64 v[202:203], v[202:203], 0, v[248:249]
	s_nop 1
	v_lshl_add_u64 v[190:191], v[224:225], 0, s[6:7]
	v_cndmask_b32_e64 v167, v191, v167, s[2:3]
	v_cndmask_b32_e64 v166, v190, v166, s[2:3]
	v_cndmask_b32_e64 v190, v165, v171, s[2:3]
	v_mov_b32_e32 v191, v225
	v_lshl_add_u64 v[190:191], s[84:85], 0, v[190:191]
;     template <int PN> DI void body(AccRef acc, const Unit& u, int wr, int wc, int fr, int fq) const {
;     ...
;                     float* lo = orow(out, l, row, PN == 8 ? O_PSK : O_PSV, PN == 8 ? O_SSK : O_SSV, 256);
; #pragma unroll
;                     for (int bj = 0; bj < 2; ++bj) {
;                         *(f32x4*)(lo + bj * 128 + cl) = (f32x4){v[bj][0], v[bj][1], v[bj][2], v[bj][3]};
;                         *(f32x4*)(lo + bj * 128 + cl + 4) = (f32x4){v[bj][4], v[bj][5], v[bj][6], v[bj][7]};
;                     }
	v_lshlrev_b64 v[166:167], 10, v[166:167]
	v_lshl_add_u64 v[166:167], v[190:191], 0, v[166:167]
	v_lshl_add_u64 v[166:167], v[166:167], 0, v[200:201]
	v_pk_fma_f32 v[192:193], v[94:95], v[172:173], v[154:155] op_sel_hi:[1,0,1]
	v_pk_fma_f32 v[190:191], v[92:93], v[172:173], v[152:153] op_sel_hi:[1,0,1]
	v_mov_b32_e32 v244, v190
	v_mov_b32_e32 v245, v191
	v_mov_b32_e32 v246, v192
	v_mov_b32_e32 v247, v193
	s_movk_i32 s6, 0xc430
	s_mov_b32 s7, -1
	v_pk_fma_f32 v[192:193], v[90:91], v[172:173], v[158:159] op_sel_hi:[1,0,1]
	v_pk_fma_f32 v[190:191], v[88:89], v[172:173], v[156:157] op_sel_hi:[1,0,1]
	s_nop 1
	v_mov_b32_dpp v248, v190 row_ror:8 row_mask:0xf bank_mask:0xf
	v_mov_b32_dpp v249, v191 row_ror:8 row_mask:0xf bank_mask:0xf
	v_mov_b32_dpp v250, v192 row_ror:8 row_mask:0xf bank_mask:0xf
	v_mov_b32_dpp v251, v193 row_ror:8 row_mask:0xf bank_mask:0xf
	v_cndmask_b32_e64 v190, v248, v244, s[98:99]
	v_cndmask_b32_e64 v191, v249, v245, s[98:99]
	v_cndmask_b32_e64 v192, v250, v246, s[98:99]
	v_cndmask_b32_e64 v193, v251, v247, s[98:99]
	v_cndmask_b32_e64 v244, v244, v248, s[98:99]
	v_cndmask_b32_e64 v245, v245, v249, s[98:99]
	v_cndmask_b32_e64 v246, v246, v250, s[98:99]
	v_cndmask_b32_e64 v247, v247, v251, s[98:99]
	v_cndmask_b32_e64 v250, 1, 0, s[98:99]
	v_cndmask_b32_e64 v251, 0, 1, s[98:99]
	v_mul_i32_i24_e32 v248, s32, v250
	v_sub_u32_e32 v249, 0, v250
	v_lshl_add_u64 v[166:167], v[166:167], 0, v[248:249]
	global_store_dwordx4 v[166:167], v[190:193], off
	v_lshl_add_u32 v248, v251, 5, s101
	v_mov_b32_e32 v249, 0
	v_lshl_add_u64 v[166:167], v[166:167], 0, v[248:249]
	global_store_dwordx4 v[166:167], v[244:247], off
	v_mul_i32_i24_e32 v248, s100, v251
	v_sub_u32_e32 v249, 0, v251
	v_lshl_add_u64 v[166:167], v[166:167], 0, v[248:249]
	v_cmp_gt_i32_e64 s[2:3], s92, v160
	v_lshl_add_u64 v[160:161], v[224:225], 0, s[6:7]
	v_pk_fma_f32 v[192:193], v[86:87], v[172:173], v[150:151] op_sel_hi:[1,0,1]
	v_pk_fma_f32 v[190:191], v[84:85], v[172:173], v[148:149] op_sel_hi:[1,0,1]
	v_mov_b32_e32 v244, v190
	v_mov_b32_e32 v245, v191
	v_mov_b32_e32 v246, v192
	v_mov_b32_e32 v247, v193
	v_pk_fma_f32 v[154:155], v[78:79], v[188:189], v[154:155] op_sel_hi:[1,0,1]
	v_pk_fma_f32 v[152:153], v[76:77], v[188:189], v[152:153] op_sel_hi:[1,0,1]
	v_pk_fma_f32 v[192:193], v[82:83], v[172:173], v[146:147] op_sel_hi:[1,0,1]
	v_pk_fma_f32 v[190:191], v[80:81], v[172:173], v[144:145] op_sel_hi:[1,0,1]
	s_nop 1
	v_mov_b32_dpp v248, v190 row_ror:8 row_mask:0xf bank_mask:0xf
	v_mov_b32_dpp v249, v191 row_ror:8 row_mask:0xf bank_mask:0xf
	v_mov_b32_dpp v250, v192 row_ror:8 row_mask:0xf bank_mask:0xf
	v_mov_b32_dpp v251, v193 row_ror:8 row_mask:0xf bank_mask:0xf
	v_cndmask_b32_e64 v190, v248, v244, s[98:99]
	v_cndmask_b32_e64 v191, v249, v245, s[98:99]
	v_cndmask_b32_e64 v192, v250, v246, s[98:99]
	v_cndmask_b32_e64 v193, v251, v247, s[98:99]
	v_cndmask_b32_e64 v244, v244, v248, s[98:99]
	v_cndmask_b32_e64 v245, v245, v249, s[98:99]
	v_cndmask_b32_e64 v246, v246, v250, s[98:99]
	v_cndmask_b32_e64 v247, v247, v251, s[98:99]
	v_cndmask_b32_e64 v250, 1, 0, s[98:99]
	v_cndmask_b32_e64 v251, 0, 1, s[98:99]
	v_mul_i32_i24_e32 v248, s32, v250
	v_sub_u32_e32 v249, 0, v250
	v_lshl_add_u64 v[166:167], v[166:167], 0, v[248:249]
	global_store_dwordx4 v[166:167], v[190:193], off offset:512
	v_lshl_add_u32 v248, v251, 5, s101
	v_mov_b32_e32 v249, 0
	v_lshl_add_u64 v[166:167], v[166:167], 0, v[248:249]
	global_store_dwordx4 v[166:167], v[244:247], off offset:512
	v_mul_i32_i24_e32 v248, s100, v251
	v_sub_u32_e32 v249, 0, v251
	v_lshl_add_u64 v[166:167], v[166:167], 0, v[248:249]
	v_lshl_add_u64 v[166:167], v[168:169], 0, s[4:5]
	v_cndmask_b32_e64 v161, v161, v167, s[2:3]
	v_cndmask_b32_e64 v160, v160, v166, s[2:3]
	v_cndmask_b32_e64 v166, v165, v171, s[2:3]
	v_mov_b32_e32 v167, v225
	v_lshl_add_u64 v[166:167], s[84:85], 0, v[166:167]
	v_lshlrev_b64 v[160:161], 10, v[160:161]
	v_lshl_add_u64 v[160:161], v[166:167], 0, v[160:161]
	v_lshl_add_u64 v[160:161], v[160:161], 0, v[200:201]
	v_mov_b32_e32 v244, v152
	v_mov_b32_e32 v245, v153
	v_mov_b32_e32 v246, v154
	v_mov_b32_e32 v247, v155
	v_pk_fma_f32 v[150:151], v[70:71], v[188:189], v[150:151] op_sel_hi:[1,0,1]
	v_pk_fma_f32 v[148:149], v[68:69], v[188:189], v[148:149] op_sel_hi:[1,0,1]
	v_pk_fma_f32 v[154:155], v[74:75], v[188:189], v[158:159] op_sel_hi:[1,0,1]
	v_pk_fma_f32 v[152:153], v[72:73], v[188:189], v[156:157] op_sel_hi:[1,0,1]
	v_pk_fma_f32 v[146:147], v[66:67], v[188:189], v[146:147] op_sel_hi:[1,0,1]
	v_pk_fma_f32 v[144:145], v[64:65], v[188:189], v[144:145] op_sel_hi:[1,0,1]
	s_nop 1
	v_mov_b32_dpp v248, v152 row_ror:8 row_mask:0xf bank_mask:0xf
	v_mov_b32_dpp v249, v153 row_ror:8 row_mask:0xf bank_mask:0xf
	v_mov_b32_dpp v250, v154 row_ror:8 row_mask:0xf bank_mask:0xf
	v_mov_b32_dpp v251, v155 row_ror:8 row_mask:0xf bank_mask:0xf
	v_cndmask_b32_e64 v152, v248, v244, s[98:99]
	v_cndmask_b32_e64 v153, v249, v245, s[98:99]
	v_cndmask_b32_e64 v154, v250, v246, s[98:99]
	v_cndmask_b32_e64 v155, v251, v247, s[98:99]
	v_cndmask_b32_e64 v244, v244, v248, s[98:99]
	v_cndmask_b32_e64 v245, v245, v249, s[98:99]
	v_cndmask_b32_e64 v246, v246, v250, s[98:99]
	v_cndmask_b32_e64 v247, v247, v251, s[98:99]
	v_cndmask_b32_e64 v250, 1, 0, s[98:99]
	v_cndmask_b32_e64 v251, 0, 1, s[98:99]
	v_mul_i32_i24_e32 v248, s32, v250
	v_sub_u32_e32 v249, 0, v250
	v_lshl_add_u64 v[160:161], v[160:161], 0, v[248:249]
	global_store_dwordx4 v[160:161], v[152:155], off
	v_lshl_add_u32 v248, v251, 5, s101
	v_mov_b32_e32 v249, 0
	v_lshl_add_u64 v[160:161], v[160:161], 0, v[248:249]
	global_store_dwordx4 v[160:161], v[244:247], off
	v_mul_i32_i24_e32 v248, s100, v251
;     template <int PN> DI void body(AccRef acc, const Unit& u, int wr, int wc, int fr, int fq) const {
;     ...
;                     float* lo = orow(out, l, row, PN == 8 ? O_PSK : O_PSV, PN == 8 ? O_SSK : O_SSV, 256);
; #pragma unroll
;                     for (int bj = 0; bj < 2; ++bj) {
;                         *(f32x4*)(lo + bj * 128 + cl) = (f32x4){v[bj][0], v[bj][1], v[bj][2], v[bj][3]};
;                         *(f32x4*)(lo + bj * 128 + cl + 4) = (f32x4){v[bj][4], v[bj][5], v[bj][6], v[bj][7]};
;                     }
	v_sub_u32_e32 v249, 0, v251
	v_lshl_add_u64 v[160:161], v[160:161], 0, v[248:249]
	v_mov_b32_e32 v244, v148
	v_mov_b32_e32 v245, v149
	v_mov_b32_e32 v246, v150
	v_mov_b32_e32 v247, v151
	s_nop 1
	v_mov_b32_dpp v248, v144 row_ror:8 row_mask:0xf bank_mask:0xf
	v_mov_b32_dpp v249, v145 row_ror:8 row_mask:0xf bank_mask:0xf
	v_mov_b32_dpp v250, v146 row_ror:8 row_mask:0xf bank_mask:0xf
	v_mov_b32_dpp v251, v147 row_ror:8 row_mask:0xf bank_mask:0xf
	v_cndmask_b32_e64 v144, v248, v244, s[98:99]
	v_cndmask_b32_e64 v145, v249, v245, s[98:99]
	v_cndmask_b32_e64 v146, v250, v246, s[98:99]
	v_cndmask_b32_e64 v147, v251, v247, s[98:99]
	v_cndmask_b32_e64 v244, v244, v248, s[98:99]
	v_cndmask_b32_e64 v245, v245, v249, s[98:99]
	v_cndmask_b32_e64 v246, v246, v250, s[98:99]
	v_cndmask_b32_e64 v247, v247, v251, s[98:99]
	v_cndmask_b32_e64 v250, 1, 0, s[98:99]
	v_cndmask_b32_e64 v251, 0, 1, s[98:99]
	v_mul_i32_i24_e32 v248, s32, v250
	v_sub_u32_e32 v249, 0, v250
	v_lshl_add_u64 v[160:161], v[160:161], 0, v[248:249]
	global_store_dwordx4 v[160:161], v[144:147], off offset:512
	v_lshl_add_u32 v248, v251, 5, s101
	v_mov_b32_e32 v249, 0
	v_lshl_add_u64 v[160:161], v[160:161], 0, v[248:249]
	global_store_dwordx4 v[160:161], v[244:247], off offset:512
	v_mul_i32_i24_e32 v248, s100, v251
	v_sub_u32_e32 v249, 0, v251
	v_lshl_add_u64 v[160:161], v[160:161], 0, v[248:249]
	s_and_saveexec_b64 s[2:3], vcc
	s_xor_b64 s[2:3], exec, s[2:3]
	v_add_u32_e32 v144, 0x400, v163
	v_mov_b32_e32 v145, v225
	s_or_saveexec_b64 s[2:3], s[2:3]
	v_mov_b64_e32 v[146:147], 0x2ae6000
	s_xor_b64 exec, exec, s[2:3]
	v_ashrrev_i32_e32 v165, 31, v164
	v_lshl_add_u64 v[144:145], v[164:165], 0, s[4:5]
	v_mov_b64_e32 v[146:147], 0x1a00000
	s_or_b64 exec, exec, s[2:3]
	v_lshlrev_b32_e32 v146, 2, v146
	v_mov_b32_e32 v147, v225
	v_lshl_add_u64 v[146:147], s[84:85], 0, v[146:147]
	v_lshlrev_b64 v[144:145], 10, v[144:145]
	v_lshl_add_u64 v[144:145], v[146:147], 0, v[144:145]
	v_lshl_add_u64 v[148:149], v[198:199], 2, v[144:145]
	s_waitcnt vmcnt(18)
	v_pk_fma_f32 v[146:147], v[62:63], v[174:175], v[142:143] op_sel_hi:[1,0,1]
	v_pk_fma_f32 v[144:145], v[60:61], v[174:175], v[140:141] op_sel_hi:[1,0,1]
	v_mov_b32_e32 v244, v144
	v_mov_b32_e32 v245, v145
	v_mov_b32_e32 v246, v146
	v_mov_b32_e32 v247, v147
	s_movk_i32 s2, 0x3fef
	v_cmp_lt_i32_e32 vcc, s2, v164
	s_waitcnt vmcnt(18)
	v_pk_fma_f32 v[146:147], v[58:59], v[174:175], v[138:139] op_sel_hi:[1,0,1]
	v_pk_fma_f32 v[144:145], v[56:57], v[174:175], v[136:137] op_sel_hi:[1,0,1]
	s_nop 1
	v_mov_b32_dpp v248, v144 row_ror:8 row_mask:0xf bank_mask:0xf
	v_mov_b32_dpp v249, v145 row_ror:8 row_mask:0xf bank_mask:0xf
	v_mov_b32_dpp v250, v146 row_ror:8 row_mask:0xf bank_mask:0xf
	v_mov_b32_dpp v251, v147 row_ror:8 row_mask:0xf bank_mask:0xf
	v_cndmask_b32_e64 v144, v248, v244, s[98:99]
	v_cndmask_b32_e64 v145, v249, v245, s[98:99]
	v_cndmask_b32_e64 v146, v250, v246, s[98:99]
	v_cndmask_b32_e64 v147, v251, v247, s[98:99]
	v_cndmask_b32_e64 v244, v244, v248, s[98:99]
	v_cndmask_b32_e64 v245, v245, v249, s[98:99]
	v_cndmask_b32_e64 v246, v246, v250, s[98:99]
	v_cndmask_b32_e64 v247, v247, v251, s[98:99]
	v_cndmask_b32_e64 v250, 1, 0, s[98:99]
	v_cndmask_b32_e64 v251, 0, 1, s[98:99]
	v_mul_i32_i24_e32 v248, s32, v250
	v_sub_u32_e32 v249, 0, v250
	v_lshl_add_u64 v[148:149], v[148:149], 0, v[248:249]
	global_store_dwordx4 v[148:149], v[144:147], off
	v_lshl_add_u32 v248, v251, 5, s101
	v_mov_b32_e32 v249, 0
	v_lshl_add_u64 v[148:149], v[148:149], 0, v[248:249]
	global_store_dwordx4 v[148:149], v[244:247], off
	v_mul_i32_i24_e32 v248, s100, v251
	v_sub_u32_e32 v249, 0, v251
	v_lshl_add_u64 v[148:149], v[148:149], 0, v[248:249]
	s_waitcnt vmcnt(17)
	s_nop 0
	v_pk_fma_f32 v[146:147], v[54:55], v[174:175], v[134:135] op_sel_hi:[1,0,1]
	v_pk_fma_f32 v[144:145], v[52:53], v[174:175], v[132:133] op_sel_hi:[1,0,1]
	v_mov_b32_e32 v244, v144
	v_mov_b32_e32 v245, v145
	v_mov_b32_e32 v246, v146
	v_mov_b32_e32 v247, v147
	s_nop 1
	v_pk_fma_f32 v[146:147], v[50:51], v[174:175], v[130:131] op_sel_hi:[1,0,1]
	v_pk_fma_f32 v[144:145], v[48:49], v[174:175], v[128:129] op_sel_hi:[1,0,1]
	s_nop 1
	v_mov_b32_dpp v248, v144 row_ror:8 row_mask:0xf bank_mask:0xf
	v_mov_b32_dpp v249, v145 row_ror:8 row_mask:0xf bank_mask:0xf
	v_mov_b32_dpp v250, v146 row_ror:8 row_mask:0xf bank_mask:0xf
	v_mov_b32_dpp v251, v147 row_ror:8 row_mask:0xf bank_mask:0xf
	v_cndmask_b32_e64 v144, v248, v244, s[98:99]
	v_cndmask_b32_e64 v145, v249, v245, s[98:99]
	v_cndmask_b32_e64 v146, v250, v246, s[98:99]
	v_cndmask_b32_e64 v147, v251, v247, s[98:99]
	v_cndmask_b32_e64 v244, v244, v248, s[98:99]
	v_cndmask_b32_e64 v245, v245, v249, s[98:99]
	v_cndmask_b32_e64 v246, v246, v250, s[98:99]
	v_cndmask_b32_e64 v247, v247, v251, s[98:99]
	v_cndmask_b32_e64 v250, 1, 0, s[98:99]
	v_cndmask_b32_e64 v251, 0, 1, s[98:99]
	v_mul_i32_i24_e32 v248, s32, v250
	v_sub_u32_e32 v249, 0, v250
	v_lshl_add_u64 v[148:149], v[148:149], 0, v[248:249]
	global_store_dwordx4 v[148:149], v[144:147], off offset:512
	v_lshl_add_u32 v248, v251, 5, s101
	v_mov_b32_e32 v249, 0
	v_lshl_add_u64 v[148:149], v[148:149], 0, v[248:249]
	global_store_dwordx4 v[148:149], v[244:247], off offset:512
	v_mul_i32_i24_e32 v248, s100, v251
	v_sub_u32_e32 v249, 0, v251
	v_lshl_add_u64 v[148:149], v[148:149], 0, v[248:249]
	s_and_saveexec_b64 s[2:3], vcc
	s_xor_b64 s[2:3], exec, s[2:3]
	s_movk_i32 s4, 0xc490
	s_mov_b32 s5, -1
	v_lshl_add_u64 v[144:145], v[224:225], 0, s[4:5]
	s_or_saveexec_b64 s[2:3], s[2:3]
	v_mov_b64_e32 v[146:147], 0x2ae6000
	s_xor_b64 exec, exec, s[2:3]
	v_add_u32_e32 v144, 0x90, v224
	v_ashrrev_i32_e32 v145, 31, v144
	s_mov_b64 s[4:5], 0x4000
;     template <int PN> DI void body(AccRef acc, const Unit& u, int wr, int wc, int fr, int fq) const {
;     ...
;                     float* lo = orow(out, l, row, PN == 8 ? O_PSK : O_PSV, PN == 8 ? O_SSK : O_SSV, 256);
; #pragma unroll
;                     for (int bj = 0; bj < 2; ++bj) {
;                         *(f32x4*)(lo + bj * 128 + cl) = (f32x4){v[bj][0], v[bj][1], v[bj][2], v[bj][3]};
;                         *(f32x4*)(lo + bj * 128 + cl + 4) = (f32x4){v[bj][4], v[bj][5], v[bj][6], v[bj][7]};
;                     }
	v_lshl_add_u64 v[144:145], v[144:145], 0, s[4:5]
	v_mov_b64_e32 v[146:147], 0x1a00000
	s_or_b64 exec, exec, s[2:3]
	v_lshlrev_b32_e32 v146, 2, v146
	v_mov_b32_e32 v147, v225
	v_lshl_add_u64 v[146:147], s[84:85], 0, v[146:147]
	v_lshlrev_b64 v[144:145], 10, v[144:145]
	v_lshl_add_u64 v[144:145], v[146:147], 0, v[144:145]
	v_lshl_add_u64 v[148:149], v[198:199], 2, v[144:145]
	v_pk_fma_f32 v[146:147], v[46:47], v[170:171], v[142:143] op_sel_hi:[1,0,1]
	v_pk_fma_f32 v[144:145], v[44:45], v[170:171], v[140:141] op_sel_hi:[1,0,1]
	v_mov_b32_e32 v244, v144
	v_mov_b32_e32 v245, v145
	v_mov_b32_e32 v246, v146
	v_mov_b32_e32 v247, v147
	s_movk_i32 s2, 0x3fdf
	v_cmp_lt_i32_e32 vcc, s2, v164
	v_pk_fma_f32 v[146:147], v[42:43], v[170:171], v[138:139] op_sel_hi:[1,0,1]
	v_pk_fma_f32 v[144:145], v[40:41], v[170:171], v[136:137] op_sel_hi:[1,0,1]
	s_nop 1
	v_mov_b32_dpp v248, v144 row_ror:8 row_mask:0xf bank_mask:0xf
	v_mov_b32_dpp v249, v145 row_ror:8 row_mask:0xf bank_mask:0xf
	v_mov_b32_dpp v250, v146 row_ror:8 row_mask:0xf bank_mask:0xf
	v_mov_b32_dpp v251, v147 row_ror:8 row_mask:0xf bank_mask:0xf
	v_cndmask_b32_e64 v144, v248, v244, s[98:99]
	v_cndmask_b32_e64 v145, v249, v245, s[98:99]
	v_cndmask_b32_e64 v146, v250, v246, s[98:99]
	v_cndmask_b32_e64 v147, v251, v247, s[98:99]
	v_cndmask_b32_e64 v244, v244, v248, s[98:99]
	v_cndmask_b32_e64 v245, v245, v249, s[98:99]
	v_cndmask_b32_e64 v246, v246, v250, s[98:99]
	v_cndmask_b32_e64 v247, v247, v251, s[98:99]
	v_cndmask_b32_e64 v250, 1, 0, s[98:99]
	v_cndmask_b32_e64 v251, 0, 1, s[98:99]
	v_mul_i32_i24_e32 v248, s32, v250
	v_sub_u32_e32 v249, 0, v250
	v_lshl_add_u64 v[148:149], v[148:149], 0, v[248:249]
	global_store_dwordx4 v[148:149], v[144:147], off
	v_lshl_add_u32 v248, v251, 5, s101
	v_mov_b32_e32 v249, 0
	v_lshl_add_u64 v[148:149], v[148:149], 0, v[248:249]
	global_store_dwordx4 v[148:149], v[244:247], off
	v_mul_i32_i24_e32 v248, s100, v251
	v_sub_u32_e32 v249, 0, v251
	v_lshl_add_u64 v[148:149], v[148:149], 0, v[248:249]
	s_nop 1
	v_pk_fma_f32 v[146:147], v[38:39], v[170:171], v[134:135] op_sel_hi:[1,0,1]
	v_pk_fma_f32 v[144:145], v[36:37], v[170:171], v[132:133] op_sel_hi:[1,0,1]
	v_mov_b32_e32 v244, v144
	v_mov_b32_e32 v245, v145
	v_mov_b32_e32 v246, v146
	v_mov_b32_e32 v247, v147
	s_nop 1
	v_pk_fma_f32 v[146:147], v[30:31], v[170:171], v[130:131] op_sel_hi:[1,0,1]
	v_pk_fma_f32 v[144:145], v[28:29], v[170:171], v[128:129] op_sel_hi:[1,0,1]
	s_nop 1
	v_mov_b32_dpp v248, v144 row_ror:8 row_mask:0xf bank_mask:0xf
	v_mov_b32_dpp v249, v145 row_ror:8 row_mask:0xf bank_mask:0xf
	v_mov_b32_dpp v250, v146 row_ror:8 row_mask:0xf bank_mask:0xf
	v_mov_b32_dpp v251, v147 row_ror:8 row_mask:0xf bank_mask:0xf
	v_cndmask_b32_e64 v144, v248, v244, s[98:99]
	v_cndmask_b32_e64 v145, v249, v245, s[98:99]
	v_cndmask_b32_e64 v146, v250, v246, s[98:99]
	v_cndmask_b32_e64 v147, v251, v247, s[98:99]
	v_cndmask_b32_e64 v244, v244, v248, s[98:99]
	v_cndmask_b32_e64 v245, v245, v249, s[98:99]
	v_cndmask_b32_e64 v246, v246, v250, s[98:99]
	v_cndmask_b32_e64 v247, v247, v251, s[98:99]
	v_cndmask_b32_e64 v250, 1, 0, s[98:99]
	v_cndmask_b32_e64 v251, 0, 1, s[98:99]
	v_mul_i32_i24_e32 v248, s32, v250
	v_sub_u32_e32 v249, 0, v250
	v_lshl_add_u64 v[148:149], v[148:149], 0, v[248:249]
	global_store_dwordx4 v[148:149], v[144:147], off offset:512
	v_lshl_add_u32 v248, v251, 5, s101
	v_mov_b32_e32 v249, 0
	v_lshl_add_u64 v[148:149], v[148:149], 0, v[248:249]
	global_store_dwordx4 v[148:149], v[244:247], off offset:512
	v_mul_i32_i24_e32 v248, s100, v251
	v_sub_u32_e32 v249, 0, v251
	v_lshl_add_u64 v[148:149], v[148:149], 0, v[248:249]
	s_and_saveexec_b64 s[2:3], vcc
	s_xor_b64 s[2:3], exec, s[2:3]
	s_movk_i32 s4, 0xc4a0
	s_mov_b32 s5, -1
	v_lshl_add_u64 v[144:145], v[224:225], 0, s[4:5]
	s_or_saveexec_b64 s[2:3], s[2:3]
	v_mov_b64_e32 v[146:147], 0x2ae6000
	s_xor_b64 exec, exec, s[2:3]
	v_add_u32_e32 v144, 0xa0, v224
	v_ashrrev_i32_e32 v145, 31, v144
	s_mov_b64 s[4:5], 0x4000
	v_lshl_add_u64 v[144:145], v[144:145], 0, s[4:5]
	v_mov_b64_e32 v[146:147], 0x1a00000
	s_or_b64 exec, exec, s[2:3]
	v_lshlrev_b32_e32 v146, 2, v146
	v_mov_b32_e32 v147, v225
	v_lshl_add_u64 v[146:147], s[84:85], 0, v[146:147]
	v_lshlrev_b64 v[144:145], 10, v[144:145]
	v_lshl_add_u64 v[144:145], v[146:147], 0, v[144:145]
	v_lshl_add_u64 v[148:149], v[198:199], 2, v[144:145]
	v_pk_fma_f32 v[146:147], v[34:35], v[196:197], v[142:143] op_sel_hi:[1,0,1]
	v_pk_fma_f32 v[144:145], v[32:33], v[196:197], v[140:141] op_sel_hi:[1,0,1]
	v_mov_b32_e32 v244, v144
	v_mov_b32_e32 v245, v145
	v_mov_b32_e32 v246, v146
	v_mov_b32_e32 v247, v147
	s_movk_i32 s2, 0x3fcf
	v_cmp_lt_i32_e32 vcc, s2, v164
	v_pk_fma_f32 v[146:147], v[26:27], v[196:197], v[138:139] op_sel_hi:[1,0,1]
	v_pk_fma_f32 v[144:145], v[24:25], v[196:197], v[136:137] op_sel_hi:[1,0,1]
	s_nop 1
	v_mov_b32_dpp v248, v144 row_ror:8 row_mask:0xf bank_mask:0xf
	v_mov_b32_dpp v249, v145 row_ror:8 row_mask:0xf bank_mask:0xf
	v_mov_b32_dpp v250, v146 row_ror:8 row_mask:0xf bank_mask:0xf
	v_mov_b32_dpp v251, v147 row_ror:8 row_mask:0xf bank_mask:0xf
	v_cndmask_b32_e64 v144, v248, v244, s[98:99]
	v_cndmask_b32_e64 v145, v249, v245, s[98:99]
	v_cndmask_b32_e64 v146, v250, v246, s[98:99]
	v_cndmask_b32_e64 v147, v251, v247, s[98:99]
	v_cndmask_b32_e64 v244, v244, v248, s[98:99]
	v_cndmask_b32_e64 v245, v245, v249, s[98:99]
	v_cndmask_b32_e64 v246, v246, v250, s[98:99]
	v_cndmask_b32_e64 v247, v247, v251, s[98:99]
	v_cndmask_b32_e64 v250, 1, 0, s[98:99]
	v_cndmask_b32_e64 v251, 0, 1, s[98:99]
	v_mul_i32_i24_e32 v248, s32, v250
	v_sub_u32_e32 v249, 0, v250
	v_lshl_add_u64 v[148:149], v[148:149], 0, v[248:249]
;     template <int PN> DI void body(AccRef acc, const Unit& u, int wr, int wc, int fr, int fq) const {
;     ...
;                     float* lo = orow(out, l, row, PN == 8 ? O_PSK : O_PSV, PN == 8 ? O_SSK : O_SSV, 256);
; #pragma unroll
;                     for (int bj = 0; bj < 2; ++bj) {
;                         *(f32x4*)(lo + bj * 128 + cl) = (f32x4){v[bj][0], v[bj][1], v[bj][2], v[bj][3]};
;                         *(f32x4*)(lo + bj * 128 + cl + 4) = (f32x4){v[bj][4], v[bj][5], v[bj][6], v[bj][7]};
;                     }
	global_store_dwordx4 v[148:149], v[144:147], off
	v_lshl_add_u32 v248, v251, 5, s101
	v_mov_b32_e32 v249, 0
	v_lshl_add_u64 v[148:149], v[148:149], 0, v[248:249]
	global_store_dwordx4 v[148:149], v[244:247], off
	v_mul_i32_i24_e32 v248, s100, v251
	v_sub_u32_e32 v249, 0, v251
	v_lshl_add_u64 v[148:149], v[148:149], 0, v[248:249]
	s_nop 1
	v_pk_fma_f32 v[146:147], v[22:23], v[196:197], v[134:135] op_sel_hi:[1,0,1]
	v_pk_fma_f32 v[144:145], v[20:21], v[196:197], v[132:133] op_sel_hi:[1,0,1]
	v_mov_b32_e32 v244, v144
	v_mov_b32_e32 v245, v145
	v_mov_b32_e32 v246, v146
	v_mov_b32_e32 v247, v147
	s_nop 1
	v_pk_fma_f32 v[146:147], v[18:19], v[196:197], v[130:131] op_sel_hi:[1,0,1]
	v_pk_fma_f32 v[144:145], v[16:17], v[196:197], v[128:129] op_sel_hi:[1,0,1]
	s_nop 1
	v_mov_b32_dpp v248, v144 row_ror:8 row_mask:0xf bank_mask:0xf
	v_mov_b32_dpp v249, v145 row_ror:8 row_mask:0xf bank_mask:0xf
	v_mov_b32_dpp v250, v146 row_ror:8 row_mask:0xf bank_mask:0xf
	v_mov_b32_dpp v251, v147 row_ror:8 row_mask:0xf bank_mask:0xf
	v_cndmask_b32_e64 v144, v248, v244, s[98:99]
	v_cndmask_b32_e64 v145, v249, v245, s[98:99]
	v_cndmask_b32_e64 v146, v250, v246, s[98:99]
	v_cndmask_b32_e64 v147, v251, v247, s[98:99]
	v_cndmask_b32_e64 v244, v244, v248, s[98:99]
	v_cndmask_b32_e64 v245, v245, v249, s[98:99]
	v_cndmask_b32_e64 v246, v246, v250, s[98:99]
	v_cndmask_b32_e64 v247, v247, v251, s[98:99]
	v_cndmask_b32_e64 v250, 1, 0, s[98:99]
	v_cndmask_b32_e64 v251, 0, 1, s[98:99]
	v_mul_i32_i24_e32 v248, s32, v250
	v_sub_u32_e32 v249, 0, v250
	v_lshl_add_u64 v[148:149], v[148:149], 0, v[248:249]
	global_store_dwordx4 v[148:149], v[144:147], off offset:512
	v_lshl_add_u32 v248, v251, 5, s101
	v_mov_b32_e32 v249, 0
	v_lshl_add_u64 v[148:149], v[148:149], 0, v[248:249]
	global_store_dwordx4 v[148:149], v[244:247], off offset:512
	v_mul_i32_i24_e32 v248, s100, v251
	v_sub_u32_e32 v249, 0, v251
	v_lshl_add_u64 v[148:149], v[148:149], 0, v[248:249]
	s_and_saveexec_b64 s[2:3], vcc
	s_xor_b64 s[2:3], exec, s[2:3]
	s_movk_i32 s4, 0xc4b0
	s_mov_b32 s5, -1
	v_lshl_add_u64 v[144:145], v[224:225], 0, s[4:5]
	s_or_saveexec_b64 s[2:3], s[2:3]
	v_mov_b64_e32 v[146:147], 0x2ae6000
	s_xor_b64 exec, exec, s[2:3]
	v_add_u32_e32 v144, 0xb0, v224
	v_ashrrev_i32_e32 v145, 31, v144
	s_mov_b64 s[4:5], 0x4000
	v_lshl_add_u64 v[144:145], v[144:145], 0, s[4:5]
	v_mov_b64_e32 v[146:147], 0x1a00000
	s_or_b64 exec, exec, s[2:3]
	v_lshlrev_b32_e32 v224, 2, v146
	v_lshl_add_u64 v[146:147], s[84:85], 0, v[224:225]
	v_lshlrev_b64 v[144:145], 10, v[144:145]
	v_lshl_add_u64 v[144:145], v[146:147], 0, v[144:145]
	v_lshl_add_u64 v[144:145], v[198:199], 2, v[144:145]
	v_pk_fma_f32 v[142:143], v[14:15], v[194:195], v[142:143] op_sel_hi:[1,0,1]
	v_pk_fma_f32 v[140:141], v[12:13], v[194:195], v[140:141] op_sel_hi:[1,0,1]
	v_pk_fma_f32 v[138:139], v[10:11], v[194:195], v[138:139] op_sel_hi:[1,0,1]
	v_pk_fma_f32 v[136:137], v[8:9], v[194:195], v[136:137] op_sel_hi:[1,0,1]
	v_pk_fma_f32 v[134:135], v[6:7], v[194:195], v[134:135] op_sel_hi:[1,0,1]
	v_pk_fma_f32 v[132:133], v[4:5], v[194:195], v[132:133] op_sel_hi:[1,0,1]
	v_pk_fma_f32 v[130:131], v[2:3], v[194:195], v[130:131] op_sel_hi:[1,0,1]
	v_pk_fma_f32 v[128:129], v[0:1], v[194:195], v[128:129] op_sel_hi:[1,0,1]
	s_mov_b64 s[80:81], 0
	v_mov_b32_e32 v244, v140
	v_mov_b32_e32 v245, v141
	v_mov_b32_e32 v246, v142
	v_mov_b32_e32 v247, v143
	s_nop 1
	v_mov_b32_dpp v248, v136 row_ror:8 row_mask:0xf bank_mask:0xf
	v_mov_b32_dpp v249, v137 row_ror:8 row_mask:0xf bank_mask:0xf
	v_mov_b32_dpp v250, v138 row_ror:8 row_mask:0xf bank_mask:0xf
	v_mov_b32_dpp v251, v139 row_ror:8 row_mask:0xf bank_mask:0xf
	v_cndmask_b32_e64 v136, v248, v244, s[98:99]
	v_cndmask_b32_e64 v137, v249, v245, s[98:99]
	v_cndmask_b32_e64 v138, v250, v246, s[98:99]
	v_cndmask_b32_e64 v139, v251, v247, s[98:99]
	v_cndmask_b32_e64 v244, v244, v248, s[98:99]
	v_cndmask_b32_e64 v245, v245, v249, s[98:99]
	v_cndmask_b32_e64 v246, v246, v250, s[98:99]
	v_cndmask_b32_e64 v247, v247, v251, s[98:99]
	v_cndmask_b32_e64 v250, 1, 0, s[98:99]
	v_cndmask_b32_e64 v251, 0, 1, s[98:99]
	v_mul_i32_i24_e32 v248, s32, v250
	v_sub_u32_e32 v249, 0, v250
	v_lshl_add_u64 v[144:145], v[144:145], 0, v[248:249]
	global_store_dwordx4 v[144:145], v[136:139], off
	v_lshl_add_u32 v248, v251, 5, s101
	v_mov_b32_e32 v249, 0
	v_lshl_add_u64 v[144:145], v[144:145], 0, v[248:249]
	global_store_dwordx4 v[144:145], v[244:247], off
	v_mul_i32_i24_e32 v248, s100, v251
	v_sub_u32_e32 v249, 0, v251
	v_lshl_add_u64 v[144:145], v[144:145], 0, v[248:249]
	v_mov_b32_e32 v244, v132
	v_mov_b32_e32 v245, v133
	v_mov_b32_e32 v246, v134
	v_mov_b32_e32 v247, v135
	s_nop 1
	v_mov_b32_dpp v248, v128 row_ror:8 row_mask:0xf bank_mask:0xf
	v_mov_b32_dpp v249, v129 row_ror:8 row_mask:0xf bank_mask:0xf
	v_mov_b32_dpp v250, v130 row_ror:8 row_mask:0xf bank_mask:0xf
	v_mov_b32_dpp v251, v131 row_ror:8 row_mask:0xf bank_mask:0xf
	v_cndmask_b32_e64 v128, v248, v244, s[98:99]
	v_cndmask_b32_e64 v129, v249, v245, s[98:99]
	v_cndmask_b32_e64 v130, v250, v246, s[98:99]
	v_cndmask_b32_e64 v131, v251, v247, s[98:99]
	v_cndmask_b32_e64 v244, v244, v248, s[98:99]
	v_cndmask_b32_e64 v245, v245, v249, s[98:99]
	v_cndmask_b32_e64 v246, v246, v250, s[98:99]
	v_cndmask_b32_e64 v247, v247, v251, s[98:99]
	v_cndmask_b32_e64 v250, 1, 0, s[98:99]
	v_cndmask_b32_e64 v251, 0, 1, s[98:99]
	v_mul_i32_i24_e32 v248, s32, v250
	v_sub_u32_e32 v249, 0, v250
	v_lshl_add_u64 v[144:145], v[144:145], 0, v[248:249]
	global_store_dwordx4 v[144:145], v[128:131], off offset:512
	v_lshl_add_u32 v248, v251, 5, s101
	v_mov_b32_e32 v249, 0
	v_lshl_add_u64 v[144:145], v[144:145], 0, v[248:249]
	global_store_dwordx4 v[144:145], v[244:247], off offset:512
	v_mul_i32_i24_e32 v248, s100, v251
	v_sub_u32_e32 v249, 0, v251
	v_lshl_add_u64 v[144:145], v[144:145], 0, v[248:249]
